# retention units: the chunk-state counter wait (device-scope poll + full L2 invalidate) is done once per workgroup and layer instead of by every unit
# speedup vs baseline: 1.0032x; 1.0032x over previous
; #define LAS __attribute__((address_space(3)))
; __device__ __forceinline__ unsigned xb_add(unsigned* p, unsigned v) { return __hip_atomic_fetch_add(p, v, __ATOMIC_RELAXED, __HIP_MEMORY_SCOPE_AGENT); }
; __device__ __forceinline__ unsigned xb_xcc_id() { return (unsigned)__builtin_amdgcn_s_getreg((3 << 11) | 20) & 0xFu; }
; #define WSB(T, off) ((T*)(kargs()->ws + (off)))
; __device__ __forceinline__ XcdBarrier xcd_barrier_post(unsigned* bar, volatile LAS unsigned* st) {
;     XcdBarrier b; b.bar = bar; b.x = xb_xcc_id(); b.st = st;
;     if (threadIdx.x == 0) (void)xb_add(&bar[XB_XCNT(b.x)], 1u);
;     return b;
; __global__ void __launch_bounds__(NT, 2) mega(Args a_unused) {
;     extern __shared__ __attribute__((aligned(16))) unsigned char lds[];
;     volatile LAS unsigned* bst = (volatile LAS unsigned*)((LAS unsigned char*)lds + LDS_BYTES - 16);
;     if (threadIdx.x < 4) bst[threadIdx.x] = 0u;
;     __syncthreads();
;     XcdBarrier bar = xcd_barrier_post(WSB(unsigned, WS_BAR), bst);
_Z4mega4Args:
	s_mov_b32 s100, 0
	s_mov_b32 s101, 0
	v_cmp_gt_u32_e32 vcc, 4, v0
	s_and_saveexec_b64 s[4:5], vcc
	v_lshl_add_u32 v1, v0, 2, 0
	v_add_u32_e32 v1, 0x23ff0, v1
	v_mov_b32_e32 v2, 0
	ds_write_b32 v1, v2
	s_or_b64 exec, exec, s[4:5]
	s_mov_b64 s[6:7], s[0:1]
	s_waitcnt lgkmcnt(0)
	s_barrier
	s_getreg_b32 s3, hwreg(HW_REG_XCC_ID, 0, 4)
	s_and_b32 s33, s3, 15
	v_cmp_eq_u32_e64 s[40:41], 0, v0
	s_and_saveexec_b64 s[4:5], s[40:41]
	s_cbranch_execz .LBB0_5
	s_mov_b64 s[8:9], exec
	v_mbcnt_lo_u32_b32 v1, s8, 0
	v_mbcnt_hi_u32_b32 v1, s9, v1
	v_cmp_eq_u32_e32 vcc, 0, v1
	s_and_b64 s[10:11], exec, vcc
	s_mov_b64 exec, s[10:11]
	s_cbranch_execz .LBB0_5
	s_load_dwordx2 s[6:7], s[6:7], 0xf8
	s_lshl_b32 s3, s33, 8
	v_mov_b32_e32 v1, 0xc0000
	s_waitcnt lgkmcnt(0)
	s_add_u32 s6, s6, s3
	s_addc_u32 s7, s7, 0
	s_bcnt1_i32_b64 s3, s[8:9]
	v_mov_b32_e32 v2, s3
	global_atomic_add v1, v2, s[6:7] offset:1024

; #define IN(i) (kargs()->in[i])
; #define WSB(T, off) ((T*)(kargs()->ws + (off)))
; #define OSB(T, off) ((T*)((unsigned char*)kargs()->out + (off)))
; __device__ __forceinline__ void ph_ret_chunk(unsigned char* lds_, bf16_t* Z, const bf16_t* KVF, const bf16_t* KVB, const float* decay_logit, const float* gn_w, int with_ctx, int u0, int ustep, unsigned* kvc, unsigned* barw) { PH_IDS;
;     ...
;     for (int u = u0; u < nunits; u += ustep) {
;         const bool lat = u < 256; const int bh = lat ? (u >> 3) : (u - 256), qb = lat ? (u & 7) : 0, b = bh >> 2, h = bh & 3;
;         const float lgf = -log1pf(__expf(-decay_logit[h])) * 1.4426950408889634f, lgb = -log1pf(__expf(-decay_logit[4 + h])) * 1.4426950408889634f;
;         const int qw0 = qb * 256 + wid * 32, qpos = qw0 + r32;
;         const int qrow = (lat ? b * 2048 : RL + b * 256) + qpos;
;         bf16_t* zq = Z + (size_t)qrow * ZW;
;         u32x4 sK[4], sV[4]; bf16x8 qf[4];
;         { const size_t rb = (lat ? (size_t)b * 2048 + qb * 256 : (size_t)RL + b * 256);
; #pragma unroll
;           for (int j = 0; j < 4; ++j) { const bf16_t* zr = Z + (rb + 64 * j + prow) * ZW + h * 64 + pc * 8; sK[j] = *(const u32x4*)(zr + C_RK); sV[j] = *(const u32x4*)(zr + C_RV); } }
; #pragma unroll
;         for (int st = 0; st < 4; ++st) qf[st] = *(const bf16x8*)(zq + C_RQ + h * 64 + 16 * st + 8 * hi);
;         if (kvc != nullptr && tid_ == 0) dep_spin(kvc, (unsigned)G_, barw);
; template <int L> __device__ __forceinline__ void layer_body(unsigned char* lds, XcdBarrier& bar) {
;     ...
;                 if (q >= Q_END) break;
;                 if (q < Q_ATTC) ph_attn_mfma(lds, QP, KP, VP, ZP, WCTX, q - Q_ATT, 1 << 20);
;                 else if (q < Q_S5) ph_attn_mfma(lds, QP, KP, VP, ZP, WCTX, 256 + q - Q_ATTC, 1 << 20);
;                 else if (q < Q_RET) ph_s5_out(lds, ZP, OSB(bf16_t, OS_TZB), OSB(bf16_t, OS_CQ), WSB(float2, WS_LP), OSB(float, OS_SLOC), WSB(float, WS_LAMT), ZP, LASTL ? 16 : 18, q - Q_S5, 1 << 20);
;                 else if (q < Q_RETC) ph_ret_chunk(lds, ZP, WSB(bf16_t, WS_KVF), OSB(bf16_t, OS_KVB), IN(I_RDEC) + l * 8, IN(I_RGN) + l * 256, WCTX, q - Q_RET, 1 << 20, kvc_, WSB(unsigned, WS_BAR));
;                 else ph_ret_chunk(lds, ZP, WSB(bf16_t, WS_KVF), OSB(bf16_t, OS_KVB), IN(I_RDEC) + l * 8, IN(I_RGN) + l * 256, WCTX, 256 + q - Q_RETC, 1 << 20, kvc_, WSB(unsigned, WS_BAR));
.LBB0_745:
	s_cmpk_gt_i32 s50, 0xff
	s_cbranch_scc0 .LBB0_1047
	s_cmpk_gt_u32 s50, 0x11f
	s_cbranch_scc0 .LBB0_1013
	s_and_b64 vcc, exec, s[4:5]
	s_cbranch_vccz .LBB0_777
	s_cmpk_gt_u32 s50, 0x33f
	s_mov_b64 s[4:5], -1
	s_cbranch_scc0 .LBB0_765
	s_mov_b64 s[4:5], s[0:1]
	s_load_dwordx2 s[4:5], s[4:5], 0xf8
	s_mov_b64 s[6:7], s[0:1]
	s_mov_b64 s[8:9], s[0:1]
	s_load_dwordx2 s[6:7], s[6:7], 0xf8
	s_waitcnt lgkmcnt(0)
	s_add_u32 s10, s4, 0x4c00000
	s_addc_u32 s11, s5, 0
	s_mov_b64 s[4:5], s[0:1]
	s_load_dwordx2 s[8:9], s[8:9], 0xf0
	s_load_dwordx2 s[14:15], s[4:5], 0xc0
	s_mov_b64 s[4:5], s[0:1]
	s_mov_b64 s[12:13], s[0:1]
	v_mov_b32_e32 v43, v0
	s_mov_b32 s16, s2
	s_load_dwordx2 s[4:5], s[4:5], 0xc8
	s_and_b32 s22, s50, 3
	v_readfirstlane_b32 s20, v43
	s_ashr_i32 s16, s20, 1
	v_mov_b32_e32 v2, s16
	s_lshl_b32 s16, s22, 2
	s_mov_b32 s23, s3
	s_add_i32 s21, s50, 0xfffffcc0
	v_mov_b32_e32 v4, s16
	s_waitcnt lgkmcnt(0)
	global_load_dword v40, v4, s[14:15]
	global_load_dword v45, v4, s[14:15] offset:16
	s_lshl_b32 s14, s21, 6
	s_and_b32 s14, s14, 0x7fffff00
	v_bfi_b32 v74, s67, v2, v43
	s_add_i32 s56, s14, 0x4000
	v_add_u32_e32 v4, s56, v74
	v_ashrrev_i32_e32 v36, 3, v43
	v_and_b32_e32 v41, 7, v43
	v_ashrrev_i32_e32 v5, 31, v4
	v_ashrrev_i32_e32 v37, 31, v36
	v_lshlrev_b32_e32 v38, 4, v41
	v_mov_b32_e32 v39, v130
	v_lshlrev_b64 v[4:5], 12, v[4:5]
	v_lshl_add_u64 v[2:3], s[10:11], 0, v[38:39]
	v_lshl_add_u64 v[34:35], s[10:11], 0, v[4:5]
	v_lshl_add_u64 v[4:5], v[36:37], 0, s[56:57]
	s_lshl_b32 s56, s22, 7
	v_lshl_add_u64 v[2:3], v[2:3], 0, s[56:57]
	v_lshlrev_b64 v[4:5], 12, v[4:5]
	v_lshl_add_u64 v[26:27], v[2:3], 0, v[4:5]
	v_add_co_u32_e32 v14, vcc, s48, v26
	v_bfe_u32 v42, v43, 5, 1
	s_nop 0
	v_addc_co_u32_e32 v15, vcc, 0, v27, vcc
	v_add_co_u32_e32 v22, vcc, s49, v26
	v_lshl_add_u64 v[34:35], v[34:35], 0, s[56:57]
	s_nop 0
	v_addc_co_u32_e32 v23, vcc, 0, v27, vcc
	v_add_co_u32_e32 v30, vcc, 0xc0000, v26
	v_lshlrev_b32_e32 v70, 4, v42
	v_mov_b32_e32 v71, v130
	v_addc_co_u32_e32 v31, vcc, 0, v27, vcc
	v_lshl_add_u64 v[140:141], v[34:35], 0, v[70:71]
	global_load_dwordx4 v[6:9], v[26:27], off offset:832
	global_load_dwordx4 v[2:5], v[26:27], off offset:1344
	global_load_dwordx4 v[10:13], v[14:15], off offset:832
	s_nop 0
	global_load_dwordx4 v[14:17], v[14:15], off offset:1344
	s_nop 0
	global_load_dwordx4 v[18:21], v[22:23], off offset:832
	s_nop 0
	global_load_dwordx4 v[22:25], v[22:23], off offset:1344
	s_nop 0
	global_load_dwordx4 v[26:29], v[30:31], off offset:832
	s_nop 0
	global_load_dwordx4 v[30:33], v[30:31], off offset:1344
	s_nop 0
	global_load_dwordx4 v[66:69], v[140:141], off offset:2880
	global_load_dwordx4 v[136:139], v[140:141], off offset:2912
	global_load_dwordx4 v[132:135], v[140:141], off offset:2944
	global_load_dwordx4 v[126:129], v[140:141], off offset:2976
	s_cmp_lg_u32 s100, 0
	s_cbranch_scc1 .Lkvc_skip_a
	v_cmp_eq_u32_e32 vcc, 0, v43
	s_and_saveexec_b64 s[10:11], vcc
	s_cbranch_execz .LBB0_764
	s_load_dwordx2 s[12:13], s[12:13], 0xf8
	global_load_dword v37, v130, s[52:53] sc1
	s_waitcnt vmcnt(0)
	v_cmp_le_u32_e32 vcc, s23, v37
	s_cbranch_vccnz .LBB0_763
	s_waitcnt lgkmcnt(0)
	s_add_u32 s12, s12, 0xc0200
	s_addc_u32 s13, s13, 0
	s_mov_b32 s24, 1
	s_branch .LBB0_753

; #define LAS __attribute__((address_space(3)))
; __device__ __forceinline__ void ph_ret_chunk(unsigned char* lds_, bf16_t* Z, const bf16_t* KVF, const bf16_t* KVB, const float* decay_logit, const float* gn_w, int with_ctx, int u0, int ustep, unsigned* kvc, unsigned* barw) { PH_IDS;
;     ...
;         const float lgf = -log1pf(__expf(-decay_logit[h])) * 1.4426950408889634f, lgb = -log1pf(__expf(-decay_logit[4 + h])) * 1.4426950408889634f;
;         const int qw0 = qb * 256 + wid * 32, qpos = qw0 + r32;
;         const int qrow = (lat ? b * 2048 : RL + b * 256) + qpos;
;         bf16_t* zq = Z + (size_t)qrow * ZW;
;         u32x4 sK[4], sV[4]; bf16x8 qf[4];
;         { const size_t rb = (lat ? (size_t)b * 2048 + qb * 256 : (size_t)RL + b * 256);
; #pragma unroll
;           for (int j = 0; j < 4; ++j) { const bf16_t* zr = Z + (rb + 64 * j + prow) * ZW + h * 64 + pc * 8; sK[j] = *(const u32x4*)(zr + C_RK); sV[j] = *(const u32x4*)(zr + C_RV); } }
; #pragma unroll
;         for (int st = 0; st < 4; ++st) qf[st] = *(const bf16x8*)(zq + C_RQ + h * 64 + 16 * st + 8 * hi);
;         if (kvc != nullptr && tid_ == 0) dep_spin(kvc, (unsigned)G_, barw);
;         __syncthreads();
; #pragma unroll
;         for (int j = 0; j < 4; ++j) { *(LAS u32x4*)(sm + j * BUF_R + koff) = sK[j]; *(LAS u32x4*)(sm + j * BUF_R + voff) = sV[j]; }
;         {
;             const float g128f = __builtin_amdgcn_exp2f(lgf * 128.f), g128b = __builtin_amdgcn_exp2f(lgb * 128.f);
;             const bf16_t* kf = KVF + (size_t)bh * 18 * 4096 + tid_ * 8; const bf16_t* kb = KVB + (size_t)bh * 18 * 4096 + tid_ * 8;
;             LAS char* sto = sm + ST_OFF + (tid_ >> 3) * KP_R + (tid_ & 7) * 16;
;             f32x4 sa = (f32x4){0.f, 0.f, 0.f, 0.f}, sb = sa, ta, tb;
.LBB0_764:
	s_or_b64 exec, exec, s[10:11]
	s_mov_b32 s100, 1
.Lkvc_skip_a:
	s_movk_i32 s11, 0x90
	v_mul_lo_u32 v71, v36, s11
	v_lshlrev_b32_e32 v37, 10, v41
	v_lshlrev_b32_e32 v76, 6, v36
	v_lshlrev_b32_e32 v36, 3, v43
	v_and_b32_e32 v75, 0x1000, v37
	v_ashrrev_i32_e32 v37, 31, v36
	v_lshlrev_b64 v[46:47], 1, v[36:37]
	s_waitcnt vmcnt(13)
	v_mul_f32_e32 v37, 0xbfb8aa3b, v40
	v_exp_f32_e32 v37, v37
	v_lshl_add_u64 v[48:49], s[6:7], 0, v[46:47]
	v_lshl_add_u64 v[40:41], s[8:9], 0, v[46:47]
	s_waitcnt vmcnt(12)
	v_mul_f32_e32 v45, 0xbfb8aa3b, v45
	v_add_f32_e32 v50, 1.0, v37
	v_add_f32_e32 v46, -1.0, v50
	v_sub_f32_e32 v47, v46, v50
	v_add_f32_e32 v47, 1.0, v47
	v_sub_f32_e32 v46, v37, v46
	v_add_f32_e32 v51, v46, v47
	v_frexp_mant_f32_e32 v52, v50
	v_cvt_f64_f32_e32 v[46:47], v50
	s_mov_b32 s6, 0x3f2aaaab
	v_exp_f32_e32 v45, v45
	v_frexp_exp_i32_f64_e32 v46, v[46:47]
	v_cmp_gt_f32_e32 vcc, s6, v52
	v_lshlrev_b32_e32 v39, 4, v43
	v_and_b32_e32 v77, 48, v39
	v_subbrev_co_u32_e32 v78, vcc, 0, v46, vcc
	v_sub_u32_e32 v47, 0, v78
	v_ldexp_f32 v46, v50, v47
	v_ldexp_f32 v50, v51, v47
	v_add_f32_e32 v47, 1.0, v45
	v_add_f32_e32 v51, -1.0, v47
	v_sub_f32_e32 v52, v51, v47
	v_add_f32_e32 v52, 1.0, v52
	v_sub_f32_e32 v51, v45, v51
	v_add_f32_e32 v51, v51, v52
	v_frexp_mant_f32_e32 v54, v47
	v_cvt_f64_f32_e32 v[52:53], v47
	v_frexp_exp_i32_f64_e32 v52, v[52:53]
	v_cmp_gt_f32_e32 vcc, s6, v54
	s_mov_b32 s6, 0x3e9b6dac
	s_nop 0
	v_subbrev_co_u32_e32 v79, vcc, 0, v52, vcc
	v_sub_u32_e32 v52, 0, v79
	v_ldexp_f32 v47, v47, v52
	v_ldexp_f32 v51, v51, v52
	v_pk_add_f32 v[52:53], v[46:47], 1.0 op_sel_hi:[1,0]
	v_pk_add_f32 v[60:61], v[46:47], -1.0 op_sel_hi:[1,0]
	v_pk_add_f32 v[54:55], v[52:53], -1.0 op_sel_hi:[1,0]
	v_pk_add_f32 v[62:63], v[60:61], 1.0 op_sel_hi:[1,0]
	v_pk_add_f32 v[54:55], v[46:47], v[54:55] neg_lo:[0,1] neg_hi:[0,1]
	v_pk_add_f32 v[46:47], v[46:47], v[62:63] neg_lo:[0,1] neg_hi:[0,1]
	v_pk_add_f32 v[54:55], v[50:51], v[54:55]
	v_pk_add_f32 v[46:47], v[50:51], v[46:47]
	v_pk_add_f32 v[56:57], v[52:53], v[54:55]
	v_pk_add_f32 v[50:51], v[60:61], v[46:47]
	v_rcp_f32_e32 v58, v56
	v_rcp_f32_e32 v59, v57
	v_pk_add_f32 v[52:53], v[56:57], v[52:53] neg_lo:[0,1] neg_hi:[0,1]
	v_pk_add_f32 v[60:61], v[50:51], v[60:61] neg_lo:[0,1] neg_hi:[0,1]
	v_pk_add_f32 v[52:53], v[54:55], v[52:53] neg_lo:[0,1] neg_hi:[0,1]
	v_pk_mul_f32 v[54:55], v[50:51], v[58:59]
	v_pk_add_f32 v[46:47], v[46:47], v[60:61] neg_lo:[0,1] neg_hi:[0,1]
	v_pk_mul_f32 v[60:61], v[56:57], v[54:55]
	s_barrier
	v_pk_fma_f32 v[62:63], v[54:55], v[56:57], v[60:61] neg_lo:[0,0,1] neg_hi:[0,0,1]
	s_nop 0
	v_pk_fma_f32 v[62:63], v[54:55], v[52:53], v[62:63]
	s_mul_i32 s56, s21, 0x12000
	v_pk_add_f32 v[64:65], v[60:61], v[62:63]
	s_add_i32 s8, 0, 0x11000
	v_pk_add_f32 v[72:73], v[50:51], v[64:65] neg_lo:[0,1] neg_hi:[0,1]
	v_pk_add_f32 v[60:61], v[64:65], v[60:61] neg_lo:[0,1] neg_hi:[0,1]
	v_pk_add_f32 v[50:51], v[50:51], v[72:73] neg_lo:[0,1] neg_hi:[0,1]
	v_and_b32_e32 v44, 31, v43
	v_pk_add_f32 v[50:51], v[50:51], v[64:65] neg_lo:[0,1] neg_hi:[0,1]
	s_lshl_b32 s10, s22, 6
	v_pk_add_f32 v[46:47], v[46:47], v[50:51]
	v_pk_add_f32 v[50:51], v[60:61], v[62:63] neg_lo:[0,1] neg_hi:[0,1]
	s_lshl_b32 s10, s10, 2
	v_pk_add_f32 v[46:47], v[50:51], v[46:47]
	v_lshlrev_b32_e32 v43, 1, v43
	v_pk_add_f32 v[50:51], v[72:73], v[46:47]
	s_nop 0
	v_pk_mul_f32 v[60:61], v[58:59], v[50:51]
	s_nop 0
	v_pk_mul_f32 v[62:63], v[56:57], v[60:61]
	s_nop 0
	v_pk_fma_f32 v[56:57], v[60:61], v[56:57], v[62:63] neg_lo:[0,0,1] neg_hi:[0,0,1]
	s_nop 0
	v_pk_fma_f32 v[52:53], v[60:61], v[52:53], v[56:57]
	v_pk_add_f32 v[56:57], v[72:73], v[50:51] neg_lo:[0,1] neg_hi:[0,1]
	s_nop 0
	v_pk_add_f32 v[46:47], v[46:47], v[56:57]
	v_pk_add_f32 v[56:57], v[62:63], v[52:53]
	s_nop 0
	v_pk_add_f32 v[64:65], v[50:51], v[56:57] neg_lo:[0,1] neg_hi:[0,1]
	v_pk_add_f32 v[62:63], v[56:57], v[62:63] neg_lo:[0,1] neg_hi:[0,1]
	v_pk_add_f32 v[50:51], v[50:51], v[64:65] neg_lo:[0,1] neg_hi:[0,1]
	s_nop 0
	v_pk_add_f32 v[50:51], v[50:51], v[56:57] neg_lo:[0,1] neg_hi:[0,1]
	s_nop 0
	v_pk_add_f32 v[46:47], v[46:47], v[50:51]
	v_pk_add_f32 v[50:51], v[62:63], v[52:53] neg_lo:[0,1] neg_hi:[0,1]
	s_nop 0
	v_pk_add_f32 v[46:47], v[50:51], v[46:47]
	v_pk_add_f32 v[50:51], v[54:55], v[60:61]
	v_pk_add_f32 v[46:47], v[64:65], v[46:47]
	v_pk_add_f32 v[52:53], v[50:51], v[54:55] neg_lo:[0,1] neg_hi:[0,1]
	v_pk_mul_f32 v[46:47], v[58:59], v[46:47]
	v_pk_add_f32 v[52:53], v[60:61], v[52:53] neg_lo:[0,1] neg_hi:[0,1]
	v_cvt_f32_i32_e32 v59, v79
	v_pk_add_f32 v[46:47], v[52:53], v[46:47]
	v_cvt_f32_i32_e32 v58, v78
	v_pk_add_f32 v[52:53], v[50:51], v[46:47]
	s_nop 0
	v_pk_mul_f32 v[54:55], v[52:53], v[52:53]
	v_pk_add_f32 v[50:51], v[52:53], v[50:51] neg_lo:[0,1] neg_hi:[0,1]
	v_pk_fma_f32 v[56:57], v[54:55], s[6:7], v[182:183] op_sel_hi:[1,0,0]
	s_mov_b32 s6, 0x3f2aaada
	v_pk_add_f32 v[46:47], v[46:47], v[50:51] neg_lo:[0,1] neg_hi:[0,1]
	v_pk_fma_f32 v[56:57], v[54:55], v[56:57], s[6:7] op_sel_hi:[1,1,0]
	s_mov_b32 s6, 0x3f317218
	v_ldexp_f32 v50, v52, 1
	v_ldexp_f32 v51, v53, 1
	v_ldexp_f32 v61, v47, 1
	v_pk_mul_f32 v[52:53], v[52:53], v[54:55]
	v_pk_mul_f32 v[54:55], v[58:59], s[6:7] op_sel_hi:[1,0]
	v_add3_u32 v47, 0, v71, v38
	v_pk_fma_f32 v[62:63], v[58:59], s[6:7], v[54:55] op_sel_hi:[1,0,1] neg_lo:[0,0,1] neg_hi:[0,0,1]
	s_mov_b32 s6, 0xb102e308
	s_waitcnt vmcnt(11)
	ds_write_b128 v47, v[6:9]
	v_add_u32_e32 v6, 0, v75
	v_pk_fma_f32 v[58:59], v[58:59], s[6:7], v[62:63] op_sel_hi:[1,0,1]
	v_add3_u32 v6, v6, v76, v77
	s_lshl_b64 s[6:7], s[56:57], 1
	s_waitcnt vmcnt(10)
	ds_write_b128 v6, v[2:5] offset:9216
	s_waitcnt vmcnt(9)
; #define LAS __attribute__((address_space(3)))
; #define ST_PUT(k) (*(LAS u32x4*)(sto + (k) * ST_SZ) = pack8(sa, sb))
; #define ST_STEP(ptr, ci_, g_) do { unpack8(*(const u32x4*)((ptr) + (size_t)(ci_) * 4096), ta, tb); sa = sa * (g_) + ta; sb = sb * (g_) + tb; } while (0)
; __device__ __forceinline__ void ph_ret_chunk(unsigned char* lds_, bf16_t* Z, const bf16_t* KVF, const bf16_t* KVB, const float* decay_logit, const float* gn_w, int with_ctx, int u0, int ustep, unsigned* kvc, unsigned* barw) { PH_IDS;
;     ...
;         for (int j = 0; j < 4; ++j) { *(LAS u32x4*)(sm + j * BUF_R + koff) = sK[j]; *(LAS u32x4*)(sm + j * BUF_R + voff) = sV[j]; }
;         {
;             const float g128f = __builtin_amdgcn_exp2f(lgf * 128.f), g128b = __builtin_amdgcn_exp2f(lgb * 128.f);
;             const bf16_t* kf = KVF + (size_t)bh * 18 * 4096 + tid_ * 8; const bf16_t* kb = KVB + (size_t)bh * 18 * 4096 + tid_ * 8;
;             LAS char* sto = sm + ST_OFF + (tid_ >> 3) * KP_R + (tid_ & 7) * 16;
;             f32x4 sa = (f32x4){0.f, 0.f, 0.f, 0.f}, sb = sa, ta, tb;
;     ...
;             if (lat) {
;                 const int cA = 2 * qb, n1 = 2 + cA, nb = 16 - cA;
;                 u32x4 Lq[9], Lr[9]; f32x4 sc = (f32x4){0.f, 0.f, 0.f, 0.f}, sd = sc;
;     ...
; #pragma unroll
;                 for (int hf = 0; hf < 2; ++hf) {
; #pragma unroll
;                     for (int k = 0; k < 9; ++k) { const int kk = 9 * hf + k;
;                         if (kk <= n1 && kk < 17) Lq[k] = *(const u32x4*)(kf + (size_t)kk * 4096);
;                         if (kk <= nb && kk < 17) Lr[k] = *(const u32x4*)(kb + (size_t)(kk == 0 ? 1 : (kk == 1 ? 0 : 19 - kk)) * 4096); }
; #pragma unroll
;                     for (int k = 0; k < 9; ++k) { const int kk = 9 * hf + k;
;                         if (kk == n1) ST_PUT(0); if (kk <= n1 && kk < 17) { unpack8(Lq[k], ta, tb); sa = sa * g128f + ta; sb = sb * g128f + tb; }
;                         if (kk == nb) ST_PUTB(3); if (kk <= nb && kk < 17) { unpack8(Lr[k], ta, tb); sc = sc * g128b + ta; sd = sd * g128b + tb; } }
;                     asm volatile("" ::: "memory"); }
;                 ST_PUT(1); ST_PUTB(2);
;     ...
;             } else {
;                 ST_PUT(0); ST_PUT(3);
;                 ST_STEP(kf, 0, g128f); ST_PUT(1);
;                 sa = (f32x4){0.f, 0.f, 0.f, 0.f}; sb = sa; ST_STEP(kb, 1, g128b); ST_PUT(2);
;             }
;     ...
;         }
;         __syncthreads();
	ds_write_b128 v47, v[10:13] offset:17408
	s_waitcnt vmcnt(8)
	ds_write_b128 v6, v[14:17] offset:26624
	s_waitcnt vmcnt(7)
	ds_write_b128 v47, v[18:21] offset:34816
	s_waitcnt vmcnt(6)
	ds_write_b128 v6, v[22:25] offset:44032
	s_waitcnt vmcnt(5)
	ds_write_b128 v47, v[26:29] offset:52224
	s_waitcnt vmcnt(4)
	ds_write_b128 v6, v[30:33] offset:61440
	v_lshl_add_u64 v[6:7], v[48:49], 0, s[6:7]
	v_add3_u32 v32, s8, v71, v38
	s_mov_b32 s8, 0x380000
	v_add_co_u32_e32 v6, vcc, s8, v6
	v_cvt_pk_bf16_f32 v2, v130, v130
	v_cvt_pk_bf16_f32 v3, v130, v130
	v_cvt_pk_bf16_f32 v4, v130, v130
	v_cvt_pk_bf16_f32 v5, v130, v130
	s_nop 1
	v_addc_co_u32_e32 v7, vcc, 0, v7, vcc
	ds_write_b128 v32, v[2:5]
	v_cvt_pk_bf16_f32 v2, v130, v130
	v_cvt_pk_bf16_f32 v3, v130, v130
	v_cvt_pk_bf16_f32 v4, v130, v130
	v_cvt_pk_bf16_f32 v5, v130, v130
	global_load_dwordx4 v[6:9], v[6:7], off
	v_pk_mul_f32 v[52:53], v[52:53], v[56:57]
	v_ldexp_f32 v46, v46, 1
	v_pk_add_f32 v[56:57], v[50:51], v[52:53]
	v_mov_b32_e32 v47, v61
	v_pk_add_f32 v[50:51], v[56:57], v[50:51] neg_lo:[0,1] neg_hi:[0,1]
	v_pk_add_f32 v[62:63], v[54:55], v[58:59]
	v_pk_add_f32 v[50:51], v[52:53], v[50:51] neg_lo:[0,1] neg_hi:[0,1]
	v_mov_b32_e32 v26, v56
	v_pk_add_f32 v[12:13], v[46:47], v[50:51]
	v_mov_b32_e32 v27, v63
	v_pk_add_f32 v[16:17], v[56:57], v[12:13]
	v_mov_b32_e32 v21, v63
	v_pk_add_f32 v[18:19], v[62:63], v[16:17]
	v_mov_b32_e32 v24, v16
	v_mov_b32_e32 v25, v19
	v_pk_add_f32 v[24:25], v[24:25], v[26:27] neg_lo:[0,1] neg_hi:[0,1]
	v_mov_b32_e32 v20, v18
	v_mov_b32_e32 v22, v62
	v_mov_b32_e32 v23, v55
	v_mov_b32_e32 v26, v62
	v_mov_b32_e32 v27, v19
	v_mov_b32_e32 v55, v25
	v_pk_add_f32 v[20:21], v[20:21], v[22:23] neg_lo:[0,1] neg_hi:[0,1]
	v_mov_b32_e32 v22, v16
	v_mov_b32_e32 v23, v59
	v_pk_add_f32 v[26:27], v[26:27], v[54:55] neg_lo:[0,1] neg_hi:[0,1]
	v_mov_b32_e32 v52, v54
	v_mov_b32_e32 v53, v51
	v_mov_b32_e32 v60, v58
	v_mov_b32_e32 v47, v13
	v_mov_b32_e32 v51, v57
	v_pk_add_f32 v[22:23], v[22:23], v[20:21] neg_lo:[0,1] neg_hi:[0,1]
	v_mov_b32_e32 v28, v26
	v_mov_b32_e32 v29, v21
	v_mov_b32_e32 v30, v18
	v_mov_b32_e32 v31, v17
	v_mov_b32_e32 v21, v57
	v_pk_add_f32 v[10:11], v[52:53], v[60:61]
	v_pk_add_f32 v[14:15], v[46:47], v[50:51]
	v_pk_add_f32 v[28:29], v[58:59], v[28:29] neg_lo:[0,1] neg_hi:[0,1]
	v_pk_add_f32 v[20:21], v[30:31], v[20:21] neg_lo:[0,1] neg_hi:[0,1]
	v_pk_add_f32 v[16:17], v[16:17], v[56:57] neg_lo:[0,1] neg_hi:[0,1]
	v_mov_b32_e32 v59, v63
	v_pk_add_f32 v[10:11], v[10:11], v[20:21] neg_lo:[0,1] neg_hi:[0,1]
	v_pk_add_f32 v[12:13], v[12:13], v[16:17] neg_lo:[0,1] neg_hi:[0,1]
	v_pk_add_f32 v[16:17], v[58:59], v[26:27] neg_lo:[0,1] neg_hi:[0,1]
	v_pk_add_f32 v[14:15], v[14:15], v[24:25] neg_lo:[0,1] neg_hi:[0,1]
	v_pk_add_f32 v[24:25], v[22:23], v[10:11]
	v_pk_add_f32 v[20:21], v[14:15], v[16:17]
	v_mov_b32_e32 v17, v23
	v_mov_b32_e32 v15, v11
	v_pk_add_f32 v[10:11], v[16:17], v[14:15]
	v_mov_b32_e32 v14, v20
	v_pk_add_f32 v[10:11], v[10:11], v[28:29] neg_lo:[0,1] neg_hi:[0,1]
	v_mov_b32_e32 v15, v25
	v_pk_add_f32 v[14:15], v[14:15], v[10:11] neg_lo:[0,1] neg_hi:[0,1]
	v_pk_add_f32 v[10:11], v[12:13], v[10:11] neg_lo:[0,1] neg_hi:[0,1]
	v_pk_add_f32 v[14:15], v[16:17], v[14:15] neg_lo:[0,1] neg_hi:[0,1]
	v_pk_add_f32 v[12:13], v[24:25], v[20:21]
	v_pk_add_f32 v[10:11], v[10:11], v[14:15]
	v_pk_add_f32 v[14:15], v[18:19], v[12:13]
	v_cmp_neq_f32_e32 vcc, s95, v37
	v_pk_add_f32 v[16:17], v[14:15], v[18:19] neg_lo:[0,1] neg_hi:[0,1]
	s_mov_b32 s8, 0xbfb8aa3b
	v_pk_add_f32 v[12:13], v[12:13], v[16:17] neg_lo:[0,1] neg_hi:[0,1]
	ds_write_b128 v32, v[2:5] offset:27648
	v_pk_add_f32 v[10:11], v[10:11], v[12:13]
	v_mul_u32_u24_e32 v71, 0x90, v44
	v_pk_add_f32 v[10:11], v[14:15], v[10:11]
	v_and_b32_e32 v52, 0xc0, v39
	v_cndmask_b32_e32 v10, v209, v10, vcc
	v_cmp_neq_f32_e32 vcc, s95, v45
	v_mul_i32_i24_e32 v53, -4, v42
	s_waitcnt vmcnt(0)
	v_lshlrev_b32_e32 v2, 16, v6
	v_cndmask_b32_e32 v11, v209, v11, vcc
	v_cmp_ngt_f32_e32 vcc, -1.0, v45
	v_and_b32_e32 v3, 0xffff0000, v6
	v_lshlrev_b32_e32 v4, 16, v7
	v_cndmask_b32_e32 v11, v210, v11, vcc
	v_cmp_ngt_f32_e32 vcc, -1.0, v37
	v_and_b32_e32 v5, 0xffff0000, v7
	v_lshlrev_b32_e32 v6, 16, v8
	v_cndmask_b32_e32 v10, v210, v10, vcc
	v_cmp_neq_f32_e32 vcc, -1.0, v37
	v_and_b32_e32 v7, 0xffff0000, v8
	v_lshlrev_b32_e32 v8, 16, v9
	v_cndmask_b32_e32 v10, v211, v10, vcc
	v_cmp_neq_f32_e32 vcc, -1.0, v45
	v_and_b32_e32 v9, 0xffff0000, v9
	s_nop 0
	v_cndmask_b32_e32 v11, v211, v11, vcc
	v_cmp_lt_f32_e64 vcc, |v45|, s96
	s_nop 1
	v_cndmask_b32_e32 v11, v11, v45, vcc
	v_cmp_lt_f32_e64 vcc, |v37|, s96
	s_nop 1
	v_cndmask_b32_e32 v10, v10, v37, vcc
	v_pk_mul_f32 v[72:73], v[10:11], s[8:9] op_sel_hi:[1,0]
	v_lshlrev_b32_e32 v37, 8, v42
	v_mul_f32_e32 v10, 0x43000000, v72
	v_exp_f32_e32 v12, v10
	v_lshl_add_u64 v[10:11], v[40:41], 0, s[6:7]
	s_mov_b32 s6, 0x1602000
	s_ashr_i32 s7, s20, 8
	v_mul_f32_e32 v12, 0, v12
	v_pk_add_f32 v[4:5], v[12:13], v[4:5] op_sel_hi:[0,1]
	v_pk_add_f32 v[2:3], v[12:13], v[2:3] op_sel_hi:[0,1]
	v_pk_add_f32 v[6:7], v[12:13], v[6:7] op_sel_hi:[0,1]
	v_cvt_pk_bf16_f32 v2, v2, v3
	v_cvt_pk_bf16_f32 v3, v4, v5
	v_cvt_pk_bf16_f32 v4, v6, v7
	v_add_co_u32_e32 v6, vcc, s6, v10
	v_pk_add_f32 v[8:9], v[12:13], v[8:9] op_sel_hi:[0,1]
	s_nop 0
	v_addc_co_u32_e32 v7, vcc, 0, v11, vcc
	v_cvt_pk_bf16_f32 v5, v8, v9
	global_load_dwordx4 v[6:9], v[6:7], off
	v_mul_f32_e32 v10, 0x43000000, v73
	v_exp_f32_e32 v10, v10
	s_mul_i32 s6, s7, 0x8800
	ds_write_b128 v32, v[2:5] offset:9216
	s_add_i32 s9, s6, 0
	v_mul_f32_e32 v10, 0, v10
	v_add3_u32 v75, s9, v71, v70
	s_lshl_b32 s6, s7, 7
	s_mulk_i32 s7, 0x2400
	s_add_i32 s7, s7, 0
	s_add_i32 s8, s7, 0x11000
	s_add_i32 s7, s7, 0x15800
	s_add_u32 s4, s4, s10
	s_addc_u32 s5, s5, 0
	s_waitcnt vmcnt(0)
	v_lshlrev_b32_e32 v2, 16, v6
	v_and_b32_e32 v3, 0xffff0000, v6
	v_lshlrev_b32_e32 v4, 16, v7
	v_and_b32_e32 v5, 0xffff0000, v7
	v_lshlrev_b32_e32 v6, 16, v8
	v_and_b32_e32 v7, 0xffff0000, v8
	v_lshlrev_b32_e32 v8, 16, v9
	v_and_b32_e32 v9, 0xffff0000, v9
	v_pk_add_f32 v[4:5], v[10:11], v[4:5] op_sel_hi:[0,1]
	v_pk_add_f32 v[2:3], v[10:11], v[2:3] op_sel_hi:[0,1]
	v_pk_add_f32 v[8:9], v[10:11], v[8:9] op_sel_hi:[0,1]
	v_pk_add_f32 v[6:7], v[10:11], v[6:7] op_sel_hi:[0,1]
	v_cvt_pk_bf16_f32 v2, v2, v3
	v_cvt_pk_bf16_f32 v3, v4, v5
	v_cvt_pk_bf16_f32 v4, v6, v7
	v_cvt_pk_bf16_f32 v5, v8, v9
	ds_write_b128 v32, v[2:5] offset:18432
	s_waitcnt lgkmcnt(0)
	s_barrier
; #define LAS __attribute__((address_space(3)))
; __device__ __forceinline__ void ret_tile_gen(const LAS char* sm, int r32, int hi, int vrd, int buf, int kp0, int qpos, float lgf, float lgb, const bf16x8 (&qf)[4], fa::f32x16& o0, fa::f32x16& o1) {
;     using namespace fa;
;     const LAS char* kb = sm + buf + r32 * KP_R + 16 * hi;
;     f32x16 p0, p1;
; #pragma unroll
;     for (int r = 0; r < 16; ++r) { p0[r] = 0.f; p1[r] = 0.f; }
; #pragma unroll
;     for (int st = 0; st < 4; ++st) {
;         const bf16x8 k0 = *(const LAS bf16x8*)(kb + 32 * st), k1 = *(const LAS bf16x8*)(kb + 32 * KP_R + 32 * st);
;         p0 = __builtin_amdgcn_mfma_f32_32x32x16_bf16(k0, qf[st], p0, 0, 0, 0);
;         p1 = __builtin_amdgcn_mfma_f32_32x32x16_bf16(k1, qf[st], p1, 0, 0, 0);
;     }
;     int d0 = qpos - kp0 - 4 * hi;
;     asm volatile("" : "+v"(d0) : "v"(p0[15]), "v"(p1[15]));
; #pragma unroll
;     for (int r = 0; r < 16; ++r) {
;         const float f0 = (float)(d0 - ((r & 3) + 8 * (r >> 2))), f1 = f0 - 32.f;
;         const float w0 = __builtin_amdgcn_exp2f(lgf * fmaxf(f0, 0.f) + lgb * fmaxf(-f0, 0.f)) * (2.f - fminf(fabsf(f0), 1.f));
;         const float w1 = __builtin_amdgcn_exp2f(lgf * fmaxf(f1, 0.f) + lgb * fmaxf(-f1, 0.f)) * (2.f - fminf(fabsf(f1), 1.f));
;         p0[r] *= w0; p1[r] *= w1;
;     }
; __device__ __forceinline__ void ph_ret_chunk(unsigned char* lds_, bf16_t* Z, const bf16_t* KVF, const bf16_t* KVB, const float* decay_logit, const float* gn_w, int with_ctx, int u0, int ustep, unsigned* kvc, unsigned* barw) { PH_IDS;
;     ...
;         u32x2 gtv[8]; f32x4 gwv[8];
; #pragma unroll
;         for (int g = 0; g < 4; ++g)
; #pragma unroll
;             for (int blk = 0; blk < 2; ++blk) { const int d = blk * 32 + 8 * g + 4 * hi; gtv[2 * g + blk] = *(const u32x2*)(zq + C_RG + h * 64 + d); gwv[2 * g + blk] = *(const f32x4*)(gn_w + h * 64 + d); }
	ds_read_b128 v[2:5], v75
	ds_read_b128 v[44:47], v75 offset:32
	ds_read_b128 v[18:21], v75 offset:4608
	ds_read_b128 v[48:51], v75 offset:4640
	s_waitcnt lgkmcnt(3)
	v_mfma_f32_32x32x16_bf16 v[2:17], v[2:5], v[66:69], 0
	ds_read_b128 v[38:41], v75 offset:64
	s_waitcnt lgkmcnt(2)
	v_mfma_f32_32x32x16_bf16 v[18:33], v[18:21], v[66:69], 0
	v_mfma_f32_32x32x16_bf16 v[2:17], v[44:47], v[136:139], v[2:17]
	s_waitcnt lgkmcnt(1)
	v_mfma_f32_32x32x16_bf16 v[18:33], v[48:51], v[136:139], v[18:33]
	ds_read_b128 v[44:47], v75 offset:4672
	ds_read_b128 v[48:51], v75 offset:96
	s_waitcnt lgkmcnt(2)
	v_mfma_f32_32x32x16_bf16 v[2:17], v[38:41], v[132:135], v[2:17]
	v_lshlrev_b32_e32 v38, 3, v42
	v_mov_b32_e32 v39, v130
	v_lshl_add_u64 v[34:35], v[34:35], 0, v[38:39]
	ds_read_b128 v[38:41], v75 offset:4704
	global_load_dwordx4 v[122:125], v70, s[4:5]
	global_load_dwordx4 v[114:117], v70, s[4:5] offset:32
	global_load_dwordx4 v[118:121], v70, s[4:5] offset:128
	global_load_dwordx4 v[110:113], v70, s[4:5] offset:160
	global_load_dwordx2 v[144:145], v[34:35], off offset:3392
	global_load_dwordx2 v[148:149], v[34:35], off offset:3408
	global_load_dwordx2 v[152:153], v[34:35], off offset:3424
	global_load_dwordx2 v[156:157], v[34:35], off offset:3440
	global_load_dwordx4 v[106:109], v70, s[4:5] offset:64
	global_load_dwordx4 v[98:101], v70, s[4:5] offset:96
	global_load_dwordx2 v[146:147], v[34:35], off offset:3456
	global_load_dwordx2 v[150:151], v[34:35], off offset:3472
	global_load_dwordx2 v[154:155], v[34:35], off offset:3488
	global_load_dwordx2 v[142:143], v[34:35], off offset:3504
	global_load_dwordx4 v[102:105], v70, s[4:5] offset:192
	global_load_dwordx4 v[94:97], v70, s[4:5] offset:224
	v_subrev_u32_e32 v34, s6, v53
	s_waitcnt lgkmcnt(2)
	v_mfma_f32_32x32x16_bf16 v[18:33], v[44:47], v[132:135], v[18:33]
	v_add_u32_e32 v77, v34, v74
	v_and_b32_e32 v34, 24, v36
	v_and_or_b32 v34, v43, 32, v34
	v_or3_b32 v46, v37, v52, v34
	v_add_u32_e32 v76, s9, v46
	s_waitcnt lgkmcnt(0)
	v_mfma_f32_32x32x16_bf16 v[18:33], v[38:41], v[126:129], v[18:33]
	v_mov_b32_e32 v38, v77
	v_mfma_f32_32x32x16_bf16 v[2:17], v[48:51], v[126:129], v[2:17]
	s_nop 0
	v_cvt_f32_i32_e32 v39, v38
	v_max_f32_e32 v34, 0, v39
	v_max_f32_e64 v35, -v39, 0
	v_pk_mul_f32 v[34:35], v[72:73], v[34:35]
	v_add_f32_e32 v36, 0xc2000000, v39
	v_add_f32_e32 v34, v34, v35
	v_exp_f32_e32 v34, v34
	v_min_f32_e64 v35, |v39|, 1.0
	v_sub_f32_e32 v35, 2.0, v35
	v_mul_f32_e32 v37, v35, v34
	v_max_f32_e32 v34, 0, v36
	v_max_f32_e64 v35, -v36, 0
	v_pk_mul_f32 v[34:35], v[72:73], v[34:35]
	v_mul_f32_e32 v37, v2, v37
	v_add_f32_e32 v34, v34, v35
	v_exp_f32_e32 v34, v34
	v_min_f32_e64 v35, |v36|, 1.0
	v_add_u32_e32 v36, -1, v38
	v_cvt_f32_i32_e32 v36, v36
	v_sub_f32_e32 v35, 2.0, v35
	v_mul_f32_e32 v34, v35, v34
	v_mul_f32_e32 v39, v18, v34
	v_max_f32_e32 v34, 0, v36
	v_max_f32_e64 v35, -v36, 0
	v_pk_mul_f32 v[34:35], v[72:73], v[34:35]
	v_add_f32_e32 v18, 0xc2000000, v36
	v_add_f32_e32 v2, v34, v35
	v_exp_f32_e32 v2, v2
	v_min_f32_e64 v34, |v36|, 1.0
	v_sub_f32_e32 v34, 2.0, v34
	v_max_f32_e64 v35, -v18, 0
	v_mul_f32_e32 v2, v34, v2
	v_max_f32_e32 v34, 0, v18
	v_pk_mul_f32 v[34:35], v[72:73], v[34:35]
	v_min_f32_e64 v18, |v18|, 1.0
	v_add_f32_e32 v34, v34, v35
	v_add_u32_e32 v35, -2, v38
	v_exp_f32_e32 v34, v34
	v_cvt_f32_i32_e32 v35, v35
	v_sub_f32_e32 v18, 2.0, v18
	v_mul_f32_e32 v18, v18, v34
	v_mul_f32_e32 v34, v3, v2
	v_max_f32_e32 v2, 0, v35
	v_max_f32_e64 v3, -v35, 0
	v_pk_mul_f32 v[2:3], v[72:73], v[2:3]
	v_mul_f32_e32 v40, v19, v18
	v_add_f32_e32 v2, v2, v3
	v_exp_f32_e32 v2, v2
	v_min_f32_e64 v3, |v35|, 1.0
	v_add_f32_e32 v18, 0xc2000000, v35
	v_sub_f32_e32 v3, 2.0, v3
	v_mul_f32_e32 v19, v3, v2
	v_max_f32_e32 v2, 0, v18
	v_max_f32_e64 v3, -v18, 0
	v_pk_mul_f32 v[2:3], v[72:73], v[2:3]
	v_mul_f32_e32 v4, v4, v19
	v_add_f32_e32 v2, v2, v3
	v_exp_f32_e32 v2, v2
	v_min_f32_e64 v3, |v18|, 1.0
	v_add_u32_e32 v18, -3, v38
	v_cvt_f32_i32_e32 v18, v18
	v_sub_f32_e32 v3, 2.0, v3
	v_mul_f32_e32 v2, v3, v2
	v_mul_f32_e32 v41, v20, v2
	v_max_f32_e32 v2, 0, v18
	v_max_f32_e64 v3, -v18, 0
	v_pk_mul_f32 v[2:3], v[72:73], v[2:3]
	v_add_f32_e32 v19, 0xc2000000, v18
	v_add_f32_e32 v2, v2, v3
	v_exp_f32_e32 v2, v2
	v_min_f32_e64 v3, |v18|, 1.0
	v_sub_f32_e32 v3, 2.0, v3
	v_mul_f32_e32 v18, v3, v2
	v_max_f32_e32 v2, 0, v19
	v_max_f32_e64 v3, -v19, 0
	v_pk_mul_f32 v[2:3], v[72:73], v[2:3]
	v_mul_f32_e32 v5, v5, v18
	v_add_f32_e32 v2, v2, v3
	v_exp_f32_e32 v2, v2
	v_min_f32_e64 v3, |v19|, 1.0
	v_add_u32_e32 v19, -8, v38
	v_cvt_f32_i32_e32 v19, v19
	v_sub_f32_e32 v3, 2.0, v3
	v_mul_f32_e32 v2, v3, v2
	v_mul_f32_e32 v42, v21, v2
	v_max_f32_e32 v2, 0, v19
	v_max_f32_e64 v3, -v19, 0
	v_pk_mul_f32 v[2:3], v[72:73], v[2:3]
	v_add_f32_e32 v18, 0xc2000000, v19
	v_add_f32_e32 v2, v2, v3
	v_exp_f32_e32 v2, v2
	v_min_f32_e64 v3, |v19|, 1.0
	v_sub_f32_e32 v3, 2.0, v3
	v_mul_f32_e32 v19, v3, v2
	v_max_f32_e32 v2, 0, v18
	v_max_f32_e64 v3, -v18, 0
	v_pk_mul_f32 v[2:3], v[72:73], v[2:3]
	v_mul_f32_e32 v6, v6, v19
	v_add_f32_e32 v2, v2, v3
	v_exp_f32_e32 v2, v2
	v_min_f32_e64 v3, |v18|, 1.0
	v_add_u32_e32 v18, -9, v38
	v_cvt_f32_i32_e32 v18, v18
	v_sub_f32_e32 v3, 2.0, v3
	v_mul_f32_e32 v2, v3, v2
	v_mul_f32_e32 v22, v22, v2
	v_max_f32_e32 v2, 0, v18
	v_max_f32_e64 v3, -v18, 0
	v_pk_mul_f32 v[2:3], v[72:73], v[2:3]
	v_add_f32_e32 v19, 0xc2000000, v18
	v_add_f32_e32 v2, v2, v3
	v_exp_f32_e32 v2, v2
	v_min_f32_e64 v3, |v18|, 1.0
	v_sub_f32_e32 v3, 2.0, v3
	v_mul_f32_e32 v18, v3, v2
	v_max_f32_e32 v2, 0, v19
	v_max_f32_e64 v3, -v19, 0
	v_pk_mul_f32 v[2:3], v[72:73], v[2:3]
	v_mul_f32_e32 v7, v7, v18
	v_add_f32_e32 v2, v2, v3
	v_exp_f32_e32 v2, v2
; #define LAS __attribute__((address_space(3)))
; __device__ __forceinline__ s16x4 vtr(const LAS char* p) { return __builtin_bit_cast(s16x4, __builtin_amdgcn_ds_read_tr16_b64_v4i16((LAS s16x4*)p)); }
; __device__ __forceinline__ bf16x8 pack_p(const f32x16& p, int base) { u32x4 w; w.x = pk2(p[base], p[base + 1]); w.y = pk2(p[base + 2], p[base + 3]); w.z = pk2(p[base + 4], p[base + 5]); w.w = pk2(p[base + 6], p[base + 7]); return __builtin_bit_cast(bf16x8, w); }
; __device__ __forceinline__ void pv_tile(f32x16& o0, f32x16& o1, const LAS char* vb, const bf16x8 (&pf)[4]) {
; #pragma unroll
;     for (int ks = 0; ks < 4; ++ks) {
;         const s16x4 a0 = vtr(vb + ks * 1024), a1 = vtr(vb + ks * 1024 + 512), b0 = vtr(vb + 4096 + ks * 1024), b1 = vtr(vb + 4096 + ks * 1024 + 512);
;         const bf16x8 v0 = (bf16x8){a0[0], a0[1], a0[2], a0[3], a1[0], a1[1], a1[2], a1[3]}, v1 = (bf16x8){b0[0], b0[1], b0[2], b0[3], b1[0], b1[1], b1[2], b1[3]};
;         o0 = __builtin_amdgcn_mfma_f32_32x32x16_bf16(v0, pf[ks], o0, 0, 0, 0);
;         o1 = __builtin_amdgcn_mfma_f32_32x32x16_bf16(v1, pf[ks], o1, 0, 0, 0);
;     }
; }
; __device__ __forceinline__ void ret_tile_gen(const LAS char* sm, int r32, int hi, int vrd, int buf, int kp0, int qpos, float lgf, float lgb, const bf16x8 (&qf)[4], fa::f32x16& o0, fa::f32x16& o1) {
;     ...
; #pragma unroll
;     for (int r = 0; r < 16; ++r) {
;         const float f0 = (float)(d0 - ((r & 3) + 8 * (r >> 2))), f1 = f0 - 32.f;
;         const float w0 = __builtin_amdgcn_exp2f(lgf * fmaxf(f0, 0.f) + lgb * fmaxf(-f0, 0.f)) * (2.f - fminf(fabsf(f0), 1.f));
;         const float w1 = __builtin_amdgcn_exp2f(lgf * fmaxf(f1, 0.f) + lgb * fmaxf(-f1, 0.f)) * (2.f - fminf(fabsf(f1), 1.f));
;         p0[r] *= w0; p1[r] *= w1;
;     }
;     bf16x8 pf[4]; pf[0] = pack_p(p0, 0); pf[1] = pack_p(p0, 8); pf[2] = pack_p(p1, 0); pf[3] = pack_p(p1, 8);
;     pv_tile(o0, o1, sm + buf + vrd, pf);
	v_min_f32_e64 v3, |v19|, 1.0
	v_add_u32_e32 v19, -10, v38
	v_cvt_f32_i32_e32 v19, v19
	v_sub_f32_e32 v3, 2.0, v3
	v_mul_f32_e32 v2, v3, v2
	v_mul_f32_e32 v23, v23, v2
	v_max_f32_e32 v2, 0, v19
	v_max_f32_e64 v3, -v19, 0
	v_pk_mul_f32 v[2:3], v[72:73], v[2:3]
	v_add_f32_e32 v18, 0xc2000000, v19
	v_add_f32_e32 v2, v2, v3
	v_exp_f32_e32 v2, v2
	v_min_f32_e64 v3, |v19|, 1.0
	v_sub_f32_e32 v3, 2.0, v3
	v_mul_f32_e32 v19, v3, v2
	v_max_f32_e32 v2, 0, v18
	v_max_f32_e64 v3, -v18, 0
	v_pk_mul_f32 v[2:3], v[72:73], v[2:3]
	v_mul_f32_e32 v8, v8, v19
	v_add_f32_e32 v2, v2, v3
	v_exp_f32_e32 v2, v2
	v_min_f32_e64 v3, |v18|, 1.0
	v_add_u32_e32 v18, -11, v38
	v_cvt_f32_i32_e32 v18, v18
	v_sub_f32_e32 v3, 2.0, v3
	v_mul_f32_e32 v2, v3, v2
	v_mul_f32_e32 v24, v24, v2
	v_max_f32_e32 v2, 0, v18
	v_max_f32_e64 v3, -v18, 0
	v_pk_mul_f32 v[2:3], v[72:73], v[2:3]
	v_add_f32_e32 v19, 0xc2000000, v18
	v_add_f32_e32 v2, v2, v3
	v_exp_f32_e32 v2, v2
	v_min_f32_e64 v3, |v18|, 1.0
	v_sub_f32_e32 v3, 2.0, v3
	v_mul_f32_e32 v18, v3, v2
	v_max_f32_e32 v2, 0, v19
	v_max_f32_e64 v3, -v19, 0
	v_pk_mul_f32 v[2:3], v[72:73], v[2:3]
	v_mul_f32_e32 v9, v9, v18
	v_add_f32_e32 v2, v2, v3
	v_exp_f32_e32 v2, v2
	v_min_f32_e64 v3, |v19|, 1.0
	v_add_u32_e32 v19, -16, v38
	v_cvt_f32_i32_e32 v19, v19
	v_sub_f32_e32 v3, 2.0, v3
	v_mul_f32_e32 v2, v3, v2
	v_mul_f32_e32 v25, v25, v2
	v_max_f32_e32 v2, 0, v19
	v_max_f32_e64 v3, -v19, 0
	v_pk_mul_f32 v[2:3], v[72:73], v[2:3]
	v_add_f32_e32 v18, 0xc2000000, v19
	v_add_f32_e32 v2, v2, v3
	v_exp_f32_e32 v2, v2
	v_min_f32_e64 v3, |v19|, 1.0
	v_sub_f32_e32 v3, 2.0, v3
	v_mul_f32_e32 v19, v3, v2
	v_max_f32_e32 v2, 0, v18
	v_max_f32_e64 v3, -v18, 0
	v_pk_mul_f32 v[2:3], v[72:73], v[2:3]
	v_mul_f32_e32 v10, v10, v19
	v_add_f32_e32 v2, v2, v3
	v_exp_f32_e32 v2, v2
	v_min_f32_e64 v3, |v18|, 1.0
	v_subrev_u32_e32 v18, 17, v38
	v_cvt_f32_i32_e32 v18, v18
	v_sub_f32_e32 v3, 2.0, v3
	v_mul_f32_e32 v2, v3, v2
	v_mul_f32_e32 v26, v26, v2
	v_max_f32_e32 v2, 0, v18
	v_max_f32_e64 v3, -v18, 0
	v_pk_mul_f32 v[2:3], v[72:73], v[2:3]
	v_add_f32_e32 v19, 0xc2000000, v18
	v_add_f32_e32 v2, v2, v3
	v_exp_f32_e32 v2, v2
	v_min_f32_e64 v3, |v18|, 1.0
	v_sub_f32_e32 v3, 2.0, v3
	v_mul_f32_e32 v18, v3, v2
	v_max_f32_e32 v2, 0, v19
	v_max_f32_e64 v3, -v19, 0
	v_pk_mul_f32 v[2:3], v[72:73], v[2:3]
	v_mul_f32_e32 v11, v11, v18
	v_add_f32_e32 v2, v2, v3
	v_exp_f32_e32 v2, v2
	v_min_f32_e64 v3, |v19|, 1.0
	v_subrev_u32_e32 v19, 18, v38
	v_cvt_f32_i32_e32 v19, v19
	v_sub_f32_e32 v3, 2.0, v3
	v_mul_f32_e32 v2, v3, v2
	v_mul_f32_e32 v27, v27, v2
	v_max_f32_e32 v2, 0, v19
	v_max_f32_e64 v3, -v19, 0
	v_pk_mul_f32 v[2:3], v[72:73], v[2:3]
	v_add_f32_e32 v18, 0xc2000000, v19
	v_add_f32_e32 v2, v2, v3
	v_exp_f32_e32 v2, v2
	v_min_f32_e64 v3, |v19|, 1.0
	v_sub_f32_e32 v3, 2.0, v3
	v_mul_f32_e32 v19, v3, v2
	v_max_f32_e32 v2, 0, v18
	v_max_f32_e64 v3, -v18, 0
	v_pk_mul_f32 v[2:3], v[72:73], v[2:3]
	v_mul_f32_e32 v12, v12, v19
	v_add_f32_e32 v2, v2, v3
	v_exp_f32_e32 v2, v2
	v_min_f32_e64 v3, |v18|, 1.0
	v_subrev_u32_e32 v18, 19, v38
	v_cvt_f32_i32_e32 v18, v18
	v_sub_f32_e32 v3, 2.0, v3
	v_mul_f32_e32 v2, v3, v2
	v_mul_f32_e32 v28, v28, v2
	v_max_f32_e32 v2, 0, v18
	v_max_f32_e64 v3, -v18, 0
	v_pk_mul_f32 v[2:3], v[72:73], v[2:3]
	v_add_f32_e32 v19, 0xc2000000, v18
	v_add_f32_e32 v2, v2, v3
	v_exp_f32_e32 v2, v2
	v_min_f32_e64 v3, |v18|, 1.0
	v_sub_f32_e32 v3, 2.0, v3
	v_mul_f32_e32 v18, v3, v2
	v_max_f32_e32 v2, 0, v19
	v_max_f32_e64 v3, -v19, 0
	v_pk_mul_f32 v[2:3], v[72:73], v[2:3]
	v_mul_f32_e32 v13, v13, v18
	v_add_f32_e32 v2, v2, v3
	v_exp_f32_e32 v2, v2
	v_min_f32_e64 v3, |v19|, 1.0
	v_subrev_u32_e32 v19, 24, v38
	v_cvt_f32_i32_e32 v19, v19
	v_sub_f32_e32 v3, 2.0, v3
	v_mul_f32_e32 v2, v3, v2
	v_mul_f32_e32 v29, v29, v2
	v_max_f32_e32 v2, 0, v19
	v_max_f32_e64 v3, -v19, 0
	v_pk_mul_f32 v[2:3], v[72:73], v[2:3]
	v_add_f32_e32 v18, 0xc2000000, v19
	v_add_f32_e32 v2, v2, v3
	v_exp_f32_e32 v2, v2
	v_min_f32_e64 v3, |v19|, 1.0
	v_sub_f32_e32 v3, 2.0, v3
	v_mul_f32_e32 v19, v3, v2
	v_max_f32_e32 v2, 0, v18
	v_max_f32_e64 v3, -v18, 0
	v_pk_mul_f32 v[2:3], v[72:73], v[2:3]
	v_mul_f32_e32 v14, v14, v19
	v_add_f32_e32 v2, v2, v3
	v_exp_f32_e32 v2, v2
	v_min_f32_e64 v3, |v18|, 1.0
	v_subrev_u32_e32 v18, 25, v38
	v_cvt_f32_i32_e32 v18, v18
	v_sub_f32_e32 v3, 2.0, v3
	v_mul_f32_e32 v2, v3, v2
	v_mul_f32_e32 v30, v30, v2
	v_max_f32_e32 v2, 0, v18
	v_max_f32_e64 v3, -v18, 0
	v_pk_mul_f32 v[2:3], v[72:73], v[2:3]
	v_add_f32_e32 v19, 0xc2000000, v18
	v_add_f32_e32 v2, v2, v3
	v_exp_f32_e32 v2, v2
	v_min_f32_e64 v3, |v18|, 1.0
	v_sub_f32_e32 v3, 2.0, v3
	v_mul_f32_e32 v18, v3, v2
	v_max_f32_e32 v2, 0, v19
	v_max_f32_e64 v3, -v19, 0
	v_pk_mul_f32 v[2:3], v[72:73], v[2:3]
	v_mul_f32_e32 v15, v15, v18
	v_add_f32_e32 v2, v2, v3
	v_exp_f32_e32 v2, v2
	v_min_f32_e64 v3, |v19|, 1.0
	v_subrev_u32_e32 v19, 26, v38
	v_cvt_f32_i32_e32 v19, v19
	v_sub_f32_e32 v3, 2.0, v3
	v_mul_f32_e32 v2, v3, v2
	v_mul_f32_e32 v31, v31, v2
	v_max_f32_e32 v2, 0, v19
	v_max_f32_e64 v3, -v19, 0
	v_pk_mul_f32 v[2:3], v[72:73], v[2:3]
	v_add_f32_e32 v18, 0xc2000000, v19
	v_add_f32_e32 v2, v2, v3
	v_exp_f32_e32 v2, v2
	v_min_f32_e64 v3, |v19|, 1.0
	v_sub_f32_e32 v3, 2.0, v3
	v_mul_f32_e32 v19, v3, v2
	v_max_f32_e32 v2, 0, v18
	v_max_f32_e64 v3, -v18, 0
	v_pk_mul_f32 v[2:3], v[72:73], v[2:3]
	v_mul_f32_e32 v16, v16, v19
	v_add_f32_e32 v2, v2, v3
	v_exp_f32_e32 v2, v2
	v_min_f32_e64 v3, |v18|, 1.0
	v_subrev_u32_e32 v18, 27, v38
	v_cvt_f32_i32_e32 v18, v18
	v_sub_f32_e32 v3, 2.0, v3
	v_mul_f32_e32 v2, v3, v2
	v_mul_f32_e32 v32, v32, v2
	v_max_f32_e32 v2, 0, v18
	v_max_f32_e64 v3, -v18, 0
	v_pk_mul_f32 v[2:3], v[72:73], v[2:3]
	v_add_f32_e32 v19, 0xc2000000, v18
	v_add_f32_e32 v2, v2, v3
	v_exp_f32_e32 v20, v2
	v_min_f32_e64 v2, |v18|, 1.0
	v_sub_f32_e32 v18, 2.0, v2
	v_max_f32_e32 v2, 0, v19
	v_max_f32_e64 v3, -v19, 0
	v_pk_mul_f32 v[2:3], v[72:73], v[2:3]
	s_nop 0
	v_add_f32_e32 v2, v2, v3
	v_exp_f32_e32 v2, v2
	v_mul_f32_e32 v3, v18, v20
	v_min_f32_e64 v18, |v19|, 1.0
	v_sub_f32_e32 v18, 2.0, v18
	v_mul_f32_e32 v2, v18, v2
	v_mul_f32_e32 v3, v17, v3
	v_mul_f32_e32 v2, v33, v2
	v_cvt_pk_bf16_f32 v18, v37, v34
	v_cvt_pk_bf16_f32 v19, v4, v5
	v_cvt_pk_bf16_f32 v20, v6, v7
	v_cvt_pk_bf16_f32 v21, v8, v9
	v_cvt_pk_bf16_f32 v34, v10, v11
	v_cvt_pk_bf16_f32 v35, v12, v13
	v_cvt_pk_bf16_f32 v36, v14, v15
	v_cvt_pk_bf16_f32 v37, v16, v3
	v_cvt_pk_bf16_f32 v38, v39, v40
	v_cvt_pk_bf16_f32 v39, v41, v42
	v_cvt_pk_bf16_f32 v40, v22, v23
	v_cvt_pk_bf16_f32 v41, v24, v25
	v_cvt_pk_bf16_f32 v42, v26, v27
	v_cvt_pk_bf16_f32 v43, v28, v29
	v_cvt_pk_bf16_f32 v44, v30, v31
	v_cvt_pk_bf16_f32 v45, v32, v2
	ds_read_b64_tr_b16 v[2:3], v76 offset:9216
	ds_read_b64_tr_b16 v[4:5], v76 offset:9728
	ds_read_b64_tr_b16 v[46:47], v76 offset:10240
	ds_read_b64_tr_b16 v[48:49], v76 offset:10752
	s_waitcnt lgkmcnt(2)
; #define LAS __attribute__((address_space(3)))
; __device__ __forceinline__ bf16x8 pack_p(const f32x16& p, int base) { u32x4 w; w.x = pk2(p[base], p[base + 1]); w.y = pk2(p[base + 2], p[base + 3]); w.z = pk2(p[base + 4], p[base + 5]); w.w = pk2(p[base + 6], p[base + 7]); return __builtin_bit_cast(bf16x8, w); }
; __device__ __forceinline__ void ret_tile_gen(const LAS char* sm, int r32, int hi, int vrd, int buf, int kp0, int qpos, float lgf, float lgb, const bf16x8 (&qf)[4], fa::f32x16& o0, fa::f32x16& o1) {
;     using namespace fa;
;     const LAS char* kb = sm + buf + r32 * KP_R + 16 * hi;
;     f32x16 p0, p1;
; #pragma unroll
;     for (int r = 0; r < 16; ++r) { p0[r] = 0.f; p1[r] = 0.f; }
; #pragma unroll
;     for (int st = 0; st < 4; ++st) {
;         const bf16x8 k0 = *(const LAS bf16x8*)(kb + 32 * st), k1 = *(const LAS bf16x8*)(kb + 32 * KP_R + 32 * st);
;         p0 = __builtin_amdgcn_mfma_f32_32x32x16_bf16(k0, qf[st], p0, 0, 0, 0);
;         p1 = __builtin_amdgcn_mfma_f32_32x32x16_bf16(k1, qf[st], p1, 0, 0, 0);
;     }
;     int d0 = qpos - kp0 - 4 * hi;
;     asm volatile("" : "+v"(d0) : "v"(p0[15]), "v"(p1[15]));
; #pragma unroll
;     for (int r = 0; r < 16; ++r) {
;         const float f0 = (float)(d0 - ((r & 3) + 8 * (r >> 2))), f1 = f0 - 32.f;
;         const float w0 = __builtin_amdgcn_exp2f(lgf * fmaxf(f0, 0.f) + lgb * fmaxf(-f0, 0.f)) * (2.f - fminf(fabsf(f0), 1.f));
;         const float w1 = __builtin_amdgcn_exp2f(lgf * fmaxf(f1, 0.f) + lgb * fmaxf(-f1, 0.f)) * (2.f - fminf(fabsf(f1), 1.f));
;         p0[r] *= w0; p1[r] *= w1;
;     }
;     bf16x8 pf[4]; pf[0] = pack_p(p0, 0); pf[1] = pack_p(p0, 8); pf[2] = pack_p(p1, 0); pf[3] = pack_p(p1, 8);
;     pv_tile(o0, o1, sm + buf + vrd, pf);
	v_mfma_f32_32x32x16_bf16 v[2:17], v[2:5], v[18:21], 0
	ds_read_b64_tr_b16 v[22:23], v76 offset:13312
	ds_read_b64_tr_b16 v[24:25], v76 offset:13824
	ds_read_b64_tr_b16 v[50:51], v76 offset:14336
	ds_read_b64_tr_b16 v[52:53], v76 offset:14848
	s_waitcnt lgkmcnt(2)
	v_mfma_f32_32x32x16_bf16 v[18:33], v[22:25], v[18:21], 0
	v_mfma_f32_32x32x16_bf16 v[2:17], v[46:49], v[34:37], v[2:17]
	s_waitcnt lgkmcnt(0)
	v_mfma_f32_32x32x16_bf16 v[18:33], v[50:53], v[34:37], v[18:33]
	ds_read_b64_tr_b16 v[34:35], v76 offset:11264
	ds_read_b64_tr_b16 v[36:37], v76 offset:11776
	ds_read_b64_tr_b16 v[46:47], v76 offset:12288
	ds_read_b64_tr_b16 v[48:49], v76 offset:12800
	s_waitcnt lgkmcnt(2)
	v_mfma_f32_32x32x16_bf16 v[2:17], v[34:37], v[38:41], v[2:17]
	ds_read_b64_tr_b16 v[34:35], v76 offset:15360
	ds_read_b64_tr_b16 v[36:37], v76 offset:15872
	ds_read_b64_tr_b16 v[50:51], v76 offset:16384
	ds_read_b64_tr_b16 v[52:53], v76 offset:16896
	s_waitcnt lgkmcnt(2)
	v_mfma_f32_32x32x16_bf16 v[18:33], v[34:37], v[38:41], v[18:33]
	v_mfma_f32_32x32x16_bf16 v[2:17], v[46:49], v[42:45], v[2:17]
	s_waitcnt lgkmcnt(0)
	v_mfma_f32_32x32x16_bf16 v[18:33], v[50:53], v[42:45], v[18:33]
	ds_read_b128 v[34:37], v75 offset:17408
	ds_read_b128 v[78:81], v75 offset:17440
	ds_read_b128 v[50:53], v75 offset:22016
	ds_read_b128 v[82:85], v75 offset:22048
	s_waitcnt lgkmcnt(3)
	v_mfma_f32_32x32x16_bf16 v[34:49], v[34:37], v[66:69], 0
	s_waitcnt lgkmcnt(1)
	v_mfma_f32_32x32x16_bf16 v[50:65], v[50:53], v[66:69], 0
	v_mfma_f32_32x32x16_bf16 v[34:49], v[78:81], v[136:139], v[34:49]
	s_waitcnt lgkmcnt(0)
	v_mfma_f32_32x32x16_bf16 v[50:65], v[82:85], v[136:139], v[50:65]
	ds_read_b128 v[78:81], v75 offset:17472
	ds_read_b128 v[82:85], v75 offset:17504
	s_waitcnt lgkmcnt(1)
	v_mfma_f32_32x32x16_bf16 v[34:49], v[78:81], v[132:135], v[34:49]
	ds_read_b128 v[78:81], v75 offset:22080
	ds_read_b128 v[86:89], v75 offset:22112
	v_subrev_u32_e32 v75, 64, v77
	s_waitcnt lgkmcnt(1)
	v_mfma_f32_32x32x16_bf16 v[50:65], v[78:81], v[132:135], v[50:65]
	v_mfma_f32_32x32x16_bf16 v[34:49], v[82:85], v[126:129], v[34:49]
	s_waitcnt lgkmcnt(0)
	v_mfma_f32_32x32x16_bf16 v[50:65], v[86:89], v[126:129], v[50:65]
	s_nop 0
	v_cvt_f32_i32_e32 v77, v75
	v_max_f32_e32 v78, 0, v77
	v_max_f32_e64 v79, -v77, 0
	v_pk_mul_f32 v[78:79], v[72:73], v[78:79]
	v_add_f32_e32 v80, 0xc2000000, v77
	v_add_f32_e32 v78, v78, v79
	v_exp_f32_e32 v78, v78
	v_min_f32_e64 v77, |v77|, 1.0
	v_sub_f32_e32 v77, 2.0, v77
	v_max_f32_e64 v79, -v80, 0
	v_mul_f32_e32 v77, v77, v78
	v_max_f32_e32 v78, 0, v80
	v_pk_mul_f32 v[78:79], v[72:73], v[78:79]
	v_mul_f32_e32 v77, v34, v77
	v_add_f32_e32 v78, v78, v79
	v_exp_f32_e32 v78, v78
	v_min_f32_e64 v79, |v80|, 1.0
	v_add_u32_e32 v80, -1, v75
	v_cvt_f32_i32_e32 v80, v80
	v_sub_f32_e32 v79, 2.0, v79
	v_mul_f32_e32 v78, v79, v78
	v_mul_f32_e32 v50, v50, v78
	v_max_f32_e32 v78, 0, v80
	v_max_f32_e64 v79, -v80, 0
	v_pk_mul_f32 v[78:79], v[72:73], v[78:79]
	v_add_f32_e32 v81, 0xc2000000, v80
	v_add_f32_e32 v34, v78, v79
	v_exp_f32_e32 v34, v34
	v_min_f32_e64 v78, |v80|, 1.0
	v_sub_f32_e32 v78, 2.0, v78
	v_max_f32_e64 v79, -v81, 0
	v_mul_f32_e32 v34, v78, v34
	v_max_f32_e32 v78, 0, v81
	v_pk_mul_f32 v[78:79], v[72:73], v[78:79]
	v_add_u32_e32 v80, -2, v75
	v_add_f32_e32 v78, v78, v79
	v_exp_f32_e32 v78, v78
	v_cvt_f32_i32_e32 v80, v80
	v_min_f32_e64 v79, |v81|, 1.0
	v_sub_f32_e32 v79, 2.0, v79
	v_mul_f32_e32 v78, v79, v78
	v_mul_f32_e32 v79, v35, v34
	v_max_f32_e32 v34, 0, v80
	v_max_f32_e64 v35, -v80, 0
	v_pk_mul_f32 v[34:35], v[72:73], v[34:35]
	v_mul_f32_e32 v51, v51, v78
	v_add_f32_e32 v34, v34, v35
	v_exp_f32_e32 v34, v34
	v_min_f32_e64 v35, |v80|, 1.0
	v_add_f32_e32 v78, 0xc2000000, v80
	v_sub_f32_e32 v35, 2.0, v35
	v_mul_f32_e32 v80, v35, v34
	v_max_f32_e32 v34, 0, v78
	v_max_f32_e64 v35, -v78, 0
	v_pk_mul_f32 v[34:35], v[72:73], v[34:35]
	v_mul_f32_e32 v36, v36, v80
	v_add_f32_e32 v34, v34, v35
	v_exp_f32_e32 v34, v34
	v_min_f32_e64 v35, |v78|, 1.0
	v_add_u32_e32 v78, -3, v75
	v_cvt_f32_i32_e32 v78, v78
	v_sub_f32_e32 v35, 2.0, v35
	v_mul_f32_e32 v34, v35, v34
	v_mul_f32_e32 v52, v52, v34
	v_max_f32_e32 v34, 0, v78
	v_max_f32_e64 v35, -v78, 0
	v_pk_mul_f32 v[34:35], v[72:73], v[34:35]
	v_add_f32_e32 v80, 0xc2000000, v78
	v_add_f32_e32 v34, v34, v35
	v_exp_f32_e32 v34, v34
	v_min_f32_e64 v35, |v78|, 1.0
	v_sub_f32_e32 v35, 2.0, v35
	v_mul_f32_e32 v78, v35, v34
	v_max_f32_e32 v34, 0, v80
	v_max_f32_e64 v35, -v80, 0
	v_pk_mul_f32 v[34:35], v[72:73], v[34:35]
	v_mul_f32_e32 v37, v37, v78
	v_add_f32_e32 v34, v34, v35
	v_exp_f32_e32 v34, v34
	v_min_f32_e64 v35, |v80|, 1.0
	v_add_u32_e32 v80, -8, v75
	v_cvt_f32_i32_e32 v80, v80
	v_sub_f32_e32 v35, 2.0, v35
	v_mul_f32_e32 v34, v35, v34
	v_mul_f32_e32 v53, v53, v34
	v_max_f32_e32 v34, 0, v80
	v_max_f32_e64 v35, -v80, 0
	v_pk_mul_f32 v[34:35], v[72:73], v[34:35]
	v_add_f32_e32 v78, 0xc2000000, v80
	v_add_f32_e32 v34, v34, v35
	v_exp_f32_e32 v34, v34
	v_min_f32_e64 v35, |v80|, 1.0
	v_sub_f32_e32 v35, 2.0, v35
	v_mul_f32_e32 v80, v35, v34
	v_max_f32_e32 v34, 0, v78
	v_max_f32_e64 v35, -v78, 0
	v_pk_mul_f32 v[34:35], v[72:73], v[34:35]
	v_mul_f32_e32 v38, v38, v80
	v_add_f32_e32 v34, v34, v35
	v_exp_f32_e32 v34, v34
	v_min_f32_e64 v35, |v78|, 1.0
	v_add_u32_e32 v78, -9, v75
	v_cvt_f32_i32_e32 v78, v78
	v_sub_f32_e32 v35, 2.0, v35
	v_mul_f32_e32 v34, v35, v34
	v_mul_f32_e32 v54, v54, v34
	v_max_f32_e32 v34, 0, v78
	v_max_f32_e64 v35, -v78, 0
	v_pk_mul_f32 v[34:35], v[72:73], v[34:35]
	v_add_f32_e32 v80, 0xc2000000, v78
	v_add_f32_e32 v34, v34, v35
	v_exp_f32_e32 v34, v34
	v_min_f32_e64 v35, |v78|, 1.0
	v_sub_f32_e32 v35, 2.0, v35
	v_mul_f32_e32 v78, v35, v34
; __device__ __forceinline__ void ret_tile_gen(const LAS char* sm, int r32, int hi, int vrd, int buf, int kp0, int qpos, float lgf, float lgb, const bf16x8 (&qf)[4], fa::f32x16& o0, fa::f32x16& o1) {
;     ...
; #pragma unroll
;     for (int r = 0; r < 16; ++r) {
;         const float f0 = (float)(d0 - ((r & 3) + 8 * (r >> 2))), f1 = f0 - 32.f;
;         const float w0 = __builtin_amdgcn_exp2f(lgf * fmaxf(f0, 0.f) + lgb * fmaxf(-f0, 0.f)) * (2.f - fminf(fabsf(f0), 1.f));
;         const float w1 = __builtin_amdgcn_exp2f(lgf * fmaxf(f1, 0.f) + lgb * fmaxf(-f1, 0.f)) * (2.f - fminf(fabsf(f1), 1.f));
;         p0[r] *= w0; p1[r] *= w1;
;     }
	v_max_f32_e32 v34, 0, v80
	v_max_f32_e64 v35, -v80, 0
	v_pk_mul_f32 v[34:35], v[72:73], v[34:35]
	v_mul_f32_e32 v39, v39, v78
	v_add_f32_e32 v34, v34, v35
	v_exp_f32_e32 v34, v34
	v_min_f32_e64 v35, |v80|, 1.0
	v_add_u32_e32 v80, -10, v75
	v_cvt_f32_i32_e32 v80, v80
	v_sub_f32_e32 v35, 2.0, v35
	v_mul_f32_e32 v34, v35, v34
	v_mul_f32_e32 v55, v55, v34
	v_max_f32_e32 v34, 0, v80
	v_max_f32_e64 v35, -v80, 0
	v_pk_mul_f32 v[34:35], v[72:73], v[34:35]
	v_add_f32_e32 v78, 0xc2000000, v80
	v_add_f32_e32 v34, v34, v35
	v_exp_f32_e32 v34, v34
	v_min_f32_e64 v35, |v80|, 1.0
	v_sub_f32_e32 v35, 2.0, v35
	v_mul_f32_e32 v80, v35, v34
	v_max_f32_e32 v34, 0, v78
	v_max_f32_e64 v35, -v78, 0
	v_pk_mul_f32 v[34:35], v[72:73], v[34:35]
	v_mul_f32_e32 v40, v40, v80
	v_add_f32_e32 v34, v34, v35
	v_exp_f32_e32 v34, v34
	v_min_f32_e64 v35, |v78|, 1.0
	v_add_u32_e32 v78, -11, v75
	v_cvt_f32_i32_e32 v78, v78
	v_sub_f32_e32 v35, 2.0, v35
	v_mul_f32_e32 v34, v35, v34
	v_mul_f32_e32 v56, v56, v34
	v_max_f32_e32 v34, 0, v78
	v_max_f32_e64 v35, -v78, 0
	v_pk_mul_f32 v[34:35], v[72:73], v[34:35]
	v_add_f32_e32 v80, 0xc2000000, v78
	v_add_f32_e32 v34, v34, v35
	v_exp_f32_e32 v34, v34
	v_min_f32_e64 v35, |v78|, 1.0
	v_sub_f32_e32 v35, 2.0, v35
	v_mul_f32_e32 v78, v35, v34
	v_max_f32_e32 v34, 0, v80
	v_max_f32_e64 v35, -v80, 0
	v_pk_mul_f32 v[34:35], v[72:73], v[34:35]
	v_mul_f32_e32 v41, v41, v78
	v_add_f32_e32 v34, v34, v35
	v_exp_f32_e32 v34, v34
	v_min_f32_e64 v35, |v80|, 1.0
	v_add_u32_e32 v80, -16, v75
	v_cvt_f32_i32_e32 v80, v80
	v_sub_f32_e32 v35, 2.0, v35
	v_mul_f32_e32 v34, v35, v34
	v_mul_f32_e32 v57, v57, v34
	v_max_f32_e32 v34, 0, v80
	v_max_f32_e64 v35, -v80, 0
	v_pk_mul_f32 v[34:35], v[72:73], v[34:35]
	v_add_f32_e32 v78, 0xc2000000, v80
	v_add_f32_e32 v34, v34, v35
	v_exp_f32_e32 v34, v34
	v_min_f32_e64 v35, |v80|, 1.0
	v_sub_f32_e32 v35, 2.0, v35
	v_mul_f32_e32 v80, v35, v34
	v_max_f32_e32 v34, 0, v78
	v_max_f32_e64 v35, -v78, 0
	v_pk_mul_f32 v[34:35], v[72:73], v[34:35]
	v_mul_f32_e32 v42, v42, v80
	v_add_f32_e32 v34, v34, v35
	v_exp_f32_e32 v34, v34
	v_min_f32_e64 v35, |v78|, 1.0
	v_subrev_u32_e32 v78, 17, v75
	v_cvt_f32_i32_e32 v78, v78
	v_sub_f32_e32 v35, 2.0, v35
	v_mul_f32_e32 v34, v35, v34
	v_mul_f32_e32 v58, v58, v34
	v_max_f32_e32 v34, 0, v78
	v_max_f32_e64 v35, -v78, 0
	v_pk_mul_f32 v[34:35], v[72:73], v[34:35]
	v_add_f32_e32 v80, 0xc2000000, v78
	v_add_f32_e32 v34, v34, v35
	v_exp_f32_e32 v34, v34
	v_min_f32_e64 v35, |v78|, 1.0
	v_sub_f32_e32 v35, 2.0, v35
	v_mul_f32_e32 v78, v35, v34
	v_max_f32_e32 v34, 0, v80
	v_max_f32_e64 v35, -v80, 0
	v_pk_mul_f32 v[34:35], v[72:73], v[34:35]
	v_mul_f32_e32 v43, v43, v78
	v_add_f32_e32 v34, v34, v35
	v_exp_f32_e32 v34, v34
	v_min_f32_e64 v35, |v80|, 1.0
	v_subrev_u32_e32 v80, 18, v75
	v_cvt_f32_i32_e32 v80, v80
	v_sub_f32_e32 v35, 2.0, v35
	v_mul_f32_e32 v34, v35, v34
	v_mul_f32_e32 v59, v59, v34
	v_max_f32_e32 v34, 0, v80
	v_max_f32_e64 v35, -v80, 0
	v_pk_mul_f32 v[34:35], v[72:73], v[34:35]
	v_add_f32_e32 v78, 0xc2000000, v80
	v_add_f32_e32 v34, v34, v35
	v_exp_f32_e32 v34, v34
	v_min_f32_e64 v35, |v80|, 1.0
	v_sub_f32_e32 v35, 2.0, v35
	v_mul_f32_e32 v80, v35, v34
	v_max_f32_e32 v34, 0, v78
	v_max_f32_e64 v35, -v78, 0
	v_pk_mul_f32 v[34:35], v[72:73], v[34:35]
	v_mul_f32_e32 v44, v44, v80
	v_add_f32_e32 v34, v34, v35
	v_exp_f32_e32 v34, v34
	v_min_f32_e64 v35, |v78|, 1.0
	v_subrev_u32_e32 v78, 19, v75
	v_cvt_f32_i32_e32 v78, v78
	v_sub_f32_e32 v35, 2.0, v35
	v_mul_f32_e32 v34, v35, v34
	v_mul_f32_e32 v60, v60, v34
	v_max_f32_e32 v34, 0, v78
	v_max_f32_e64 v35, -v78, 0
	v_pk_mul_f32 v[34:35], v[72:73], v[34:35]
	v_add_f32_e32 v80, 0xc2000000, v78
	v_add_f32_e32 v34, v34, v35
	v_exp_f32_e32 v34, v34
	v_min_f32_e64 v35, |v78|, 1.0
	v_sub_f32_e32 v35, 2.0, v35
	v_mul_f32_e32 v78, v35, v34
	v_max_f32_e32 v34, 0, v80
	v_max_f32_e64 v35, -v80, 0
	v_pk_mul_f32 v[34:35], v[72:73], v[34:35]
	v_mul_f32_e32 v45, v45, v78
	v_add_f32_e32 v34, v34, v35
	v_exp_f32_e32 v34, v34
	v_min_f32_e64 v35, |v80|, 1.0
	v_subrev_u32_e32 v80, 24, v75
	v_cvt_f32_i32_e32 v80, v80
	v_sub_f32_e32 v35, 2.0, v35
	v_mul_f32_e32 v34, v35, v34
	v_mul_f32_e32 v61, v61, v34
	v_max_f32_e32 v34, 0, v80
	v_max_f32_e64 v35, -v80, 0
	v_pk_mul_f32 v[34:35], v[72:73], v[34:35]
	v_add_f32_e32 v78, 0xc2000000, v80
	v_add_f32_e32 v34, v34, v35
	v_exp_f32_e32 v34, v34
	v_min_f32_e64 v35, |v80|, 1.0
	v_sub_f32_e32 v35, 2.0, v35
	v_mul_f32_e32 v80, v35, v34
	v_max_f32_e32 v34, 0, v78
	v_max_f32_e64 v35, -v78, 0
	v_pk_mul_f32 v[34:35], v[72:73], v[34:35]
	v_mul_f32_e32 v46, v46, v80
	v_add_f32_e32 v34, v34, v35
	v_exp_f32_e32 v34, v34
	v_min_f32_e64 v35, |v78|, 1.0
	v_subrev_u32_e32 v78, 25, v75
	v_cvt_f32_i32_e32 v78, v78
	v_sub_f32_e32 v35, 2.0, v35
	v_mul_f32_e32 v34, v35, v34
	v_mul_f32_e32 v62, v62, v34
	v_max_f32_e32 v34, 0, v78
	v_max_f32_e64 v35, -v78, 0
	v_pk_mul_f32 v[34:35], v[72:73], v[34:35]
	v_add_f32_e32 v80, 0xc2000000, v78
	v_add_f32_e32 v34, v34, v35
	v_exp_f32_e32 v34, v34
	v_min_f32_e64 v35, |v78|, 1.0
	v_sub_f32_e32 v35, 2.0, v35
	v_mul_f32_e32 v78, v35, v34
	v_max_f32_e32 v34, 0, v80
	v_max_f32_e64 v35, -v80, 0
	v_pk_mul_f32 v[34:35], v[72:73], v[34:35]
	v_mul_f32_e32 v47, v47, v78
	v_add_f32_e32 v34, v34, v35
	v_exp_f32_e32 v34, v34
	v_min_f32_e64 v35, |v80|, 1.0
	v_subrev_u32_e32 v80, 26, v75
	v_cvt_f32_i32_e32 v80, v80
	v_sub_f32_e32 v35, 2.0, v35
	v_mul_f32_e32 v34, v35, v34
	v_mul_f32_e32 v63, v63, v34
	v_max_f32_e32 v34, 0, v80
	v_max_f32_e64 v35, -v80, 0
	v_pk_mul_f32 v[34:35], v[72:73], v[34:35]
	v_add_f32_e32 v78, 0xc2000000, v80
	v_add_f32_e32 v34, v34, v35
	v_exp_f32_e32 v34, v34
	v_min_f32_e64 v35, |v80|, 1.0
; __device__ __forceinline__ bf16x8 pack_p(const f32x16& p, int base) { u32x4 w; w.x = pk2(p[base], p[base + 1]); w.y = pk2(p[base + 2], p[base + 3]); w.z = pk2(p[base + 4], p[base + 5]); w.w = pk2(p[base + 6], p[base + 7]); return __builtin_bit_cast(bf16x8, w); }
; __device__ __forceinline__ void ret_tile_gen(const LAS char* sm, int r32, int hi, int vrd, int buf, int kp0, int qpos, float lgf, float lgb, const bf16x8 (&qf)[4], fa::f32x16& o0, fa::f32x16& o1) {
;     ...
; #pragma unroll
;     for (int r = 0; r < 16; ++r) {
;         const float f0 = (float)(d0 - ((r & 3) + 8 * (r >> 2))), f1 = f0 - 32.f;
;         const float w0 = __builtin_amdgcn_exp2f(lgf * fmaxf(f0, 0.f) + lgb * fmaxf(-f0, 0.f)) * (2.f - fminf(fabsf(f0), 1.f));
;         const float w1 = __builtin_amdgcn_exp2f(lgf * fmaxf(f1, 0.f) + lgb * fmaxf(-f1, 0.f)) * (2.f - fminf(fabsf(f1), 1.f));
;         p0[r] *= w0; p1[r] *= w1;
;     }
;     bf16x8 pf[4]; pf[0] = pack_p(p0, 0); pf[1] = pack_p(p0, 8); pf[2] = pack_p(p1, 0); pf[3] = pack_p(p1, 8);
;     pv_tile(o0, o1, sm + buf + vrd, pf);
; __device__ __forceinline__ void ph_ret_chunk(unsigned char* lds_, bf16_t* Z, const bf16_t* KVF, const bf16_t* KVB, const float* decay_logit, const float* gn_w, int with_ctx, int u0, int ustep, unsigned* kvc, unsigned* barw) { PH_IDS;
;     ...
;         { f32x16 p0, p1;
;           ret_qk(sm, r32, hi, ST_OFF + cl * ST_SZ, qf, p0, p1);
;           const float sf = __builtin_amdgcn_exp2f(lgf * (float)(qpos - c0 + 1));
; #pragma unroll
;           for (int r = 0; r < 16; ++r) { o0[r] += p0[r] * sf; o1[r] += p1[r] * sf; }
	v_sub_f32_e32 v35, 2.0, v35
	v_subrev_u32_e32 v75, 27, v75
	v_mul_f32_e32 v80, v35, v34
	v_max_f32_e32 v34, 0, v78
	v_max_f32_e64 v35, -v78, 0
	v_pk_mul_f32 v[34:35], v[72:73], v[34:35]
	v_cvt_f32_i32_e32 v75, v75
	v_add_f32_e32 v34, v34, v35
	v_exp_f32_e32 v34, v34
	v_min_f32_e64 v35, |v78|, 1.0
	v_sub_f32_e32 v35, 2.0, v35
	v_mul_f32_e32 v48, v48, v80
	v_mul_f32_e32 v34, v35, v34
	v_mul_f32_e32 v64, v64, v34
	v_max_f32_e32 v34, 0, v75
	v_max_f32_e64 v35, -v75, 0
	v_pk_mul_f32 v[34:35], v[72:73], v[34:35]
	v_add_f32_e32 v78, 0xc2000000, v75
	v_add_f32_e32 v34, v34, v35
	v_exp_f32_e32 v80, v34
	v_min_f32_e64 v34, |v75|, 1.0
	v_sub_f32_e32 v75, 2.0, v34
	v_max_f32_e32 v34, 0, v78
	v_max_f32_e64 v35, -v78, 0
	v_pk_mul_f32 v[34:35], v[72:73], v[34:35]
	s_nop 0
	v_add_f32_e32 v34, v34, v35
	v_exp_f32_e32 v34, v34
	v_mul_f32_e32 v35, v75, v80
	v_min_f32_e64 v75, |v78|, 1.0
	v_sub_f32_e32 v75, 2.0, v75
	v_mul_f32_e32 v34, v75, v34
	v_mul_f32_e32 v49, v49, v35
	v_mul_f32_e32 v65, v65, v34
	v_cvt_pk_bf16_f32 v34, v77, v79
	v_cvt_pk_bf16_f32 v35, v36, v37
	v_cvt_pk_bf16_f32 v36, v38, v39
	v_cvt_pk_bf16_f32 v37, v40, v41
	v_cvt_pk_bf16_f32 v38, v42, v43
	v_cvt_pk_bf16_f32 v39, v44, v45
	v_cvt_pk_bf16_f32 v40, v46, v47
	v_cvt_pk_bf16_f32 v41, v48, v49
	v_cvt_pk_bf16_f32 v42, v50, v51
	v_cvt_pk_bf16_f32 v43, v52, v53
	v_cvt_pk_bf16_f32 v44, v54, v55
	v_cvt_pk_bf16_f32 v45, v56, v57
	v_cvt_pk_bf16_f32 v46, v58, v59
	v_cvt_pk_bf16_f32 v47, v60, v61
	v_cvt_pk_bf16_f32 v48, v62, v63
	v_cvt_pk_bf16_f32 v49, v64, v65
	ds_read_b64_tr_b16 v[50:51], v76 offset:26624
	ds_read_b64_tr_b16 v[52:53], v76 offset:27136
	ds_read_b64_tr_b16 v[54:55], v76 offset:27648
	ds_read_b64_tr_b16 v[56:57], v76 offset:28160
	s_waitcnt lgkmcnt(2)
	v_mfma_f32_32x32x16_bf16 v[2:17], v[50:53], v[34:37], v[2:17]
	ds_read_b64_tr_b16 v[50:51], v76 offset:30720
	ds_read_b64_tr_b16 v[52:53], v76 offset:31232
	ds_read_b64_tr_b16 v[58:59], v76 offset:31744
	ds_read_b64_tr_b16 v[60:61], v76 offset:32256
	s_waitcnt lgkmcnt(2)
	v_mfma_f32_32x32x16_bf16 v[18:33], v[50:53], v[34:37], v[18:33]
	v_mfma_f32_32x32x16_bf16 v[2:17], v[54:57], v[38:41], v[2:17]
	s_waitcnt lgkmcnt(0)
	v_mfma_f32_32x32x16_bf16 v[18:33], v[58:61], v[38:41], v[18:33]
	ds_read_b64_tr_b16 v[34:35], v76 offset:28672
	ds_read_b64_tr_b16 v[36:37], v76 offset:29184
	ds_read_b64_tr_b16 v[38:39], v76 offset:29696
	ds_read_b64_tr_b16 v[40:41], v76 offset:30208
	s_waitcnt lgkmcnt(2)
	v_mfma_f32_32x32x16_bf16 v[2:17], v[34:37], v[42:45], v[2:17]
	ds_read_b64_tr_b16 v[34:35], v76 offset:32768
	ds_read_b64_tr_b16 v[36:37], v76 offset:33280
	ds_read_b64_tr_b16 v[50:51], v76 offset:33792
	ds_read_b64_tr_b16 v[52:53], v76 offset:34304
	s_waitcnt lgkmcnt(2)
	v_mfma_f32_32x32x16_bf16 v[18:33], v[34:37], v[42:45], v[18:33]
	v_mfma_f32_32x32x16_bf16 v[2:17], v[38:41], v[46:49], v[2:17]
	s_waitcnt lgkmcnt(0)
	v_mfma_f32_32x32x16_bf16 v[18:33], v[50:53], v[46:49], v[18:33]
	v_add3_u32 v75, s8, v71, v70
	ds_read_b128 v[34:37], v75
	ds_read_b128 v[76:79], v75 offset:32
	ds_read_b128 v[50:53], v75 offset:4608
	ds_read_b128 v[80:83], v75 offset:4640
	v_add3_u32 v70, s7, v71, v70
	s_waitcnt lgkmcnt(1)
	v_mfma_f32_32x32x16_bf16 v[50:65], v[50:53], v[66:69], 0
	v_mfma_f32_32x32x16_bf16 v[34:49], v[34:37], v[66:69], 0
	s_waitcnt lgkmcnt(0)
	v_mfma_f32_32x32x16_bf16 v[50:65], v[80:83], v[136:139], v[50:65]
	v_mfma_f32_32x32x16_bf16 v[34:49], v[76:79], v[136:139], v[34:49]
	ds_read_b128 v[76:79], v75 offset:4672
	ds_read_b128 v[80:83], v75 offset:4704
	ds_read_b128 v[162:165], v75 offset:64
	ds_read_b128 v[166:169], v75 offset:96
	v_subrev_u32_e32 v75, s6, v74
	v_add_u32_e32 v75, 1, v75
	v_cvt_f32_i32_e32 v75, v75
	v_mul_f32_e32 v71, v72, v75
	s_waitcnt lgkmcnt(3)
	v_mfma_f32_32x32x16_bf16 v[50:65], v[76:79], v[132:135], v[50:65]
	ds_read_b128 v[76:79], v70 offset:4608
	ds_read_b128 v[170:173], v70
	ds_read_b128 v[174:177], v70 offset:32
	ds_read_b128 v[178:181], v70 offset:4640
	v_exp_f32_e32 v158, v71
	v_sub_u32_e32 v71, s6, v74
	v_add_u32_e32 v71, 0x80, v71
	v_cvt_f32_i32_e32 v71, v71
	v_xor_b32_e32 v72, 32, v1
	s_waitcnt lgkmcnt(6)
	v_mfma_f32_32x32x16_bf16 v[50:65], v[80:83], v[126:129], v[50:65]
	s_waitcnt lgkmcnt(3)
	v_mfma_f32_32x32x16_bf16 v[78:93], v[76:79], v[66:69], 0
	ds_read_b128 v[184:187], v70 offset:64
	ds_read_b128 v[188:191], v70 offset:96
	ds_read_b128 v[74:77], v70 offset:4672
	ds_read_b128 v[192:195], v70 offset:4704
	v_mul_f32_e32 v70, v73, v71
	v_exp_f32_e32 v160, v70
	v_and_b32_e32 v70, 64, v1
	v_add_u32_e32 v73, 64, v70
	s_nop 1
	v_pk_fma_f32 v[32:33], v[158:159], v[64:65], v[32:33] op_sel_hi:[0,1,1]
	v_pk_fma_f32 v[30:31], v[158:159], v[62:63], v[30:31] op_sel_hi:[0,1,1]
	s_waitcnt lgkmcnt(4)
	v_mfma_f32_32x32x16_bf16 v[78:93], v[178:181], v[136:139], v[78:93]
	s_waitcnt vmcnt(2)
	v_lshlrev_b32_e32 v178, 16, v142
	v_and_b32_e32 v179, 0xffff0000, v142
	v_mul_f32_e32 v70, 0xbfb8aa3b, v178
	v_mul_f32_e32 v71, 0xbfb8aa3b, v179
	v_exp_f32_e32 v70, v70
	v_exp_f32_e32 v71, v71
	v_cmp_lt_i32_e32 vcc, v72, v73
	s_waitcnt lgkmcnt(1)
	v_mfma_f32_32x32x16_bf16 v[78:93], v[74:77], v[132:135], v[78:93]
	v_add_f32_e64 v180, v70, 1.0
	v_add_f32_e64 v181, v71, 1.0
	v_div_scale_f32 v64, s[4:5], v181, v181, 1.0
	v_rcp_f32_e32 v65, v64
	v_cndmask_b32_e32 v72, v1, v72, vcc
	v_lshlrev_b32_e32 v131, 2, v72
	s_waitcnt lgkmcnt(0)
; __device__ __forceinline__ void ph_ret_chunk(unsigned char* lds_, bf16_t* Z, const bf16_t* KVF, const bf16_t* KVB, const float* decay_logit, const float* gn_w, int with_ctx, int u0, int ustep, unsigned* kvc, unsigned* barw) { PH_IDS;
;     ...
;         { f32x16 p0, p1;
;           ret_qk(sm, r32, hi, ST_OFF + cl * ST_SZ, qf, p0, p1);
;           const float sf = __builtin_amdgcn_exp2f(lgf * (float)(qpos - c0 + 1));
; #pragma unroll
;           for (int r = 0; r < 16; ++r) { o0[r] += p0[r] * sf; o1[r] += p1[r] * sf; }
;           ret_qk(sm, r32, hi, ST_OFF + (2 + cl) * ST_SZ, qf, p0, p1);
;           const float sbk = __builtin_amdgcn_exp2f(lgb * (float)(c0 + 128 - qpos));
; #pragma unroll
;           for (int r = 0; r < 16; ++r) { o0[r] += p0[r] * sbk; o1[r] += p1[r] * sbk; } }
	v_mfma_f32_32x32x16_bf16 v[78:93], v[192:195], v[126:129], v[78:93]
	v_mfma_f32_32x32x16_bf16 v[34:49], v[162:165], v[132:135], v[34:49]
	s_nop 10
	v_fma_f32 v90, v160, v90, v30
	v_fma_f32 v91, v160, v91, v31
	v_fma_f32 v30, -v64, v65, 1.0
	v_fmac_f32_e32 v65, v30, v65
	v_div_scale_f32 v30, vcc, 1.0, v181, 1.0
	v_mul_f32_e32 v31, v30, v65
	v_fma_f32 v62, -v64, v31, v30
	v_mfma_f32_32x32x16_bf16 v[62:77], v[170:173], v[66:69], 0
	v_fma_f32 v32, v160, v92, v32
	v_fma_f32 v33, v160, v93, v33
	v_div_scale_f32 v92, s[4:5], v180, v180, 1.0
	v_rcp_f32_e32 v93, v92
	v_rcp_f32_e32 v31, v181
	v_fma_f32 v30, -v92, v93, 1.0
	v_mfma_f32_32x32x16_bf16 v[62:77], v[174:177], v[136:139], v[62:77]
	v_fmac_f32_e32 v93, v30, v93
	v_div_scale_f32 v30, vcc, 1.0, v180, 1.0
	v_mul_f32_e32 v142, v30, v93
	v_fma_f32 v159, -v92, v142, v30
	v_mfma_f32_32x32x16_bf16 v[62:77], v[184:187], v[132:135], v[62:77]
	v_lshlrev_b32_e32 v92, 16, v157
	v_and_b32_e32 v93, 0xffff0000, v157
	v_mul_f32_e32 v136, 0xbfb8aa3b, v92
	v_mul_f32_e32 v137, 0xbfb8aa3b, v93
	v_exp_f32_e32 v136, v136
	v_exp_f32_e32 v137, v137
	v_mfma_f32_32x32x16_bf16 v[34:49], v[166:169], v[126:129], v[34:49]
	v_fma_f32 v28, v158, v60, v28
	v_fma_f32 v29, v158, v61, v29
	v_fma_f32 v60, v160, v88, v28
	v_fma_f32 v61, v160, v89, v29
	v_add_f32_e64 v132, v136, 1.0
	v_add_f32_e64 v133, v137, 1.0
	v_pk_fma_f32 v[26:27], v[158:159], v[58:59], v[26:27] op_sel_hi:[0,1,1]
	v_mfma_f32_32x32x16_bf16 v[62:77], v[188:191], v[126:129], v[62:77]
	s_nop 1
	s_nop 1
	v_fma_f32 v16, v158, v48, v16
	v_fma_f32 v17, v158, v49, v17
	v_lshlrev_b32_e32 v126, 16, v156
	v_and_b32_e32 v127, 0xffff0000, v156
	v_fma_f32 v14, v158, v46, v14
	v_fma_f32 v15, v158, v47, v15
	v_pk_fma_f32 v[58:59], v[160:161], v[86:87], v[26:27] op_sel_hi:[0,1,1]
	v_pk_fma_f32 v[12:13], v[158:159], v[44:45], v[12:13] op_sel_hi:[0,1,1]
	v_pk_fma_f32 v[10:11], v[158:159], v[42:43], v[10:11] op_sel_hi:[0,1,1]
	s_nop 0
	v_pk_fma_f32 v[48:49], v[160:161], v[76:77], v[16:17] op_sel_hi:[0,1,1]
	v_rcp_f32_e32 v17, v133
	v_mul_f32_e32 v76, 0xbfb8aa3b, v126
	v_mul_f32_e32 v77, 0xbfb8aa3b, v127
	v_exp_f32_e32 v76, v76
	v_exp_f32_e32 v77, v77
	v_rcp_f32_e32 v16, v132
	s_nop 0
	v_pk_mul_f32 v[16:17], v[16:17], v[92:93]
	v_pk_add_f32 v[92:93], v[76:77], 1.0 op_sel_hi:[1,0]
	v_pk_fma_f32 v[46:47], v[160:161], v[74:75], v[14:15] op_sel_hi:[0,1,1]
	v_pk_fma_f32 v[44:45], v[160:161], v[72:73], v[12:13] op_sel_hi:[0,1,1]
	v_pk_fma_f32 v[42:43], v[160:161], v[70:71], v[10:11] op_sel_hi:[0,1,1]
	v_pk_fma_f32 v[24:25], v[158:159], v[56:57], v[24:25] op_sel_hi:[0,1,1]
	v_rcp_f32_e32 v15, v93
	v_lshlrev_b32_e32 v128, 16, v155
	v_and_b32_e32 v129, 0xffff0000, v155
	v_mul_f32_e32 v74, 0xbfb8aa3b, v128
	v_mul_f32_e32 v75, 0xbfb8aa3b, v129
	v_exp_f32_e32 v74, v74
	v_exp_f32_e32 v75, v75
	v_rcp_f32_e32 v14, v92
	s_nop 0
	v_pk_mul_f32 v[14:15], v[14:15], v[126:127]
	v_pk_add_f32 v[92:93], v[74:75], 1.0 op_sel_hi:[1,0]
	v_pk_fma_f32 v[56:57], v[160:161], v[84:85], v[24:25] op_sel_hi:[0,1,1]
	v_pk_fma_f32 v[22:23], v[158:159], v[54:55], v[22:23] op_sel_hi:[0,1,1]
	v_pk_fma_f32 v[54:55], v[160:161], v[82:83], v[22:23] op_sel_hi:[0,1,1]
	v_pk_fma_f32 v[8:9], v[158:159], v[40:41], v[8:9] op_sel_hi:[0,1,1]
	v_rcp_f32_e32 v29, v93
	v_lshlrev_b32_e32 v88, 16, v154
	v_and_b32_e32 v89, 0xffff0000, v154
	v_mul_f32_e32 v126, 0xbfb8aa3b, v88
	v_mul_f32_e32 v127, 0xbfb8aa3b, v89
	v_exp_f32_e32 v126, v126
	v_exp_f32_e32 v127, v127
	v_rcp_f32_e32 v28, v92
	s_nop 0
	v_pk_mul_f32 v[28:29], v[28:29], v[128:129]
	v_pk_add_f32 v[92:93], v[126:127], 1.0 op_sel_hi:[1,0]
	v_pk_fma_f32 v[40:41], v[160:161], v[68:69], v[8:9] op_sel_hi:[0,1,1]
	v_pk_fma_f32 v[6:7], v[158:159], v[38:39], v[6:7] op_sel_hi:[0,1,1]
	v_pk_fma_f32 v[38:39], v[160:161], v[66:67], v[6:7] op_sel_hi:[0,1,1]
	v_pk_fma_f32 v[20:21], v[158:159], v[52:53], v[20:21] op_sel_hi:[0,1,1]
	v_rcp_f32_e32 v27, v93
	v_lshlrev_b32_e32 v86, 16, v153
	v_and_b32_e32 v87, 0xffff0000, v153
	v_mul_f32_e32 v126, 0xbfb8aa3b, v86
	v_mul_f32_e32 v127, 0xbfb8aa3b, v87
	v_exp_f32_e32 v126, v126
	v_exp_f32_e32 v127, v127
	v_rcp_f32_e32 v26, v92
	s_nop 0
	v_pk_mul_f32 v[26:27], v[26:27], v[88:89]
	v_pk_add_f32 v[92:93], v[126:127], 1.0 op_sel_hi:[1,0]
	v_lshlrev_b32_e32 v88, 16, v152
	v_and_b32_e32 v89, 0xffff0000, v152
	v_pk_fma_f32 v[20:21], v[160:161], v[80:81], v[20:21] op_sel_hi:[0,1,1]
	v_pk_fma_f32 v[18:19], v[158:159], v[50:51], v[18:19] op_sel_hi:[0,1,1]
	v_rcp_f32_e32 v13, v93
	v_pk_fma_f32 v[18:19], v[160:161], v[78:79], v[18:19] op_sel_hi:[0,1,1]
	v_mul_f32_e32 v72, 0xbfb8aa3b, v88
	v_mul_f32_e32 v73, 0xbfb8aa3b, v89
	v_exp_f32_e32 v72, v72
	v_exp_f32_e32 v73, v73
	v_rcp_f32_e32 v12, v92
	s_nop 0
	v_pk_mul_f32 v[12:13], v[12:13], v[86:87]
	v_pk_add_f32 v[86:87], v[72:73], 1.0 op_sel_hi:[1,0]
	v_pk_fma_f32 v[4:5], v[158:159], v[36:37], v[4:5] op_sel_hi:[0,1,1]
	v_pk_fma_f32 v[4:5], v[160:161], v[64:65], v[4:5] op_sel_hi:[0,1,1]
	v_pk_fma_f32 v[2:3], v[158:159], v[34:35], v[2:3] op_sel_hi:[0,1,1]
	v_pk_fma_f32 v[2:3], v[160:161], v[62:63], v[2:3] op_sel_hi:[0,1,1]
	v_rcp_f32_e32 v11, v87
	v_lshlrev_b32_e32 v92, 16, v151
	v_and_b32_e32 v93, 0xffff0000, v151
	v_mul_f32_e32 v70, 0xbfb8aa3b, v92
	v_mul_f32_e32 v71, 0xbfb8aa3b, v93
	v_exp_f32_e32 v70, v70
	v_exp_f32_e32 v71, v71
	v_rcp_f32_e32 v10, v86
	s_nop 0
	v_pk_mul_f32 v[10:11], v[10:11], v[88:89]
	v_pk_add_f32 v[86:87], v[70:71], 1.0 op_sel_hi:[1,0]
	v_pk_add_f32 v[70:71], v[42:43], v[58:59]
	v_pk_add_f32 v[72:73], v[44:45], v[60:61]
	v_pk_add_f32 v[74:75], v[46:47], v[90:91]
	v_pk_add_f32 v[76:77], v[48:49], v[32:33]
	v_rcp_f32_e32 v25, v87
	v_lshlrev_b32_e32 v84, 16, v150
	v_and_b32_e32 v85, 0xffff0000, v150
; __device__ __forceinline__ float siluf_(float x) { return x * sigmoidf_(x); }
; __device__ __forceinline__ void ph_ret_chunk(unsigned char* lds_, bf16_t* Z, const bf16_t* KVF, const bf16_t* KVB, const float* decay_logit, const float* gn_w, int with_ctx, int u0, int ustep, unsigned* kvc, unsigned* barw) { PH_IDS;
;     ...
;         float s1 = 0.f;
; #pragma unroll
;         for (int r = 0; r < 16; ++r) s1 += o0[r] + o1[r];
;         s1 += __shfl_xor(s1, 32);
;         const float mu = s1 * (1.f / 64);
;         float s2 = 0.f;
; #pragma unroll
;         for (int r = 0; r < 16; ++r) { const float a = o0[r] - mu, c = o1[r] - mu; s2 += a * a + c * c; }
;         s2 += __shfl_xor(s2, 32);
;         const float rstd = rsqrtf(s2 * (1.f / 64) + EPS);
;         u32x2 wv[2][4];
; #pragma unroll
;         for (int g = 0; g < 4; ++g)
; #pragma unroll
;             for (int blk = 0; blk < 2; ++blk) {
;                 const int d = blk * 32 + 8 * g + 4 * hi;
;                 const u32x2 gt = gtv[2 * g + blk];
;                 const f32x4 gw = gwv[2 * g + blk];
;                 float y[4];
; #pragma unroll
;                 for (int q = 0; q < 4; ++q) { const float ov = blk ? o1[4 * g + q] : o0[4 * g + q]; const unsigned gb = q < 2 ? gt.x : gt.y; const float gv = __uint_as_float((q & 1) ? (gb & 0xffff0000u) : (gb << 16));
;                     y[q] = siluf_(gv) * ((ov - mu) * rstd * gw[q]); }
	v_mul_f32_e32 v88, 0xbfb8aa3b, v84
	v_mul_f32_e32 v89, 0xbfb8aa3b, v85
	v_exp_f32_e32 v88, v88
	v_exp_f32_e32 v89, v89
	v_rcp_f32_e32 v24, v86
	s_nop 0
	v_pk_mul_f32 v[24:25], v[24:25], v[92:93]
	v_pk_add_f32 v[86:87], v[88:89], 1.0 op_sel_hi:[1,0]
	v_rcp_f32_e32 v30, v180
	s_nop 0
	v_pk_mul_f32 v[30:31], v[30:31], v[178:179]
	v_rcp_f32_e32 v23, v87
	v_lshlrev_b32_e32 v82, 16, v149
	v_and_b32_e32 v83, 0xffff0000, v149
	v_mul_f32_e32 v88, 0xbfb8aa3b, v82
	v_mul_f32_e32 v89, 0xbfb8aa3b, v83
	v_exp_f32_e32 v88, v88
	v_exp_f32_e32 v89, v89
	v_rcp_f32_e32 v22, v86
	s_nop 0
	v_pk_mul_f32 v[22:23], v[22:23], v[84:85]
	v_pk_add_f32 v[86:87], v[88:89], 1.0 op_sel_hi:[1,0]
	v_lshlrev_b32_e32 v84, 16, v148
	v_and_b32_e32 v85, 0xffff0000, v148
	v_rcp_f32_e32 v9, v87
	v_mul_f32_e32 v68, 0xbfb8aa3b, v84
	v_mul_f32_e32 v69, 0xbfb8aa3b, v85
	v_exp_f32_e32 v68, v68
	v_exp_f32_e32 v69, v69
	v_rcp_f32_e32 v8, v86
	s_nop 0
	v_pk_mul_f32 v[8:9], v[8:9], v[82:83]
	v_pk_add_f32 v[82:83], v[68:69], 1.0 op_sel_hi:[1,0]
	v_pk_add_f32 v[68:69], v[40:41], v[56:57]
	s_nop 0
	v_rcp_f32_e32 v7, v83
	v_lshlrev_b32_e32 v66, 16, v147
	v_and_b32_e32 v67, 0xffff0000, v147
	v_mul_f32_e32 v86, 0xbfb8aa3b, v66
	v_mul_f32_e32 v87, 0xbfb8aa3b, v67
	v_exp_f32_e32 v86, v86
	v_exp_f32_e32 v87, v87
	v_rcp_f32_e32 v6, v82
	s_nop 0
	v_pk_mul_f32 v[6:7], v[6:7], v[84:85]
	v_pk_add_f32 v[82:83], v[86:87], 1.0 op_sel_hi:[1,0]
	v_pk_add_f32 v[84:85], v[38:39], v[54:55]
	s_nop 0
	v_rcp_f32_e32 v53, v83
	v_lshlrev_b32_e32 v80, 16, v146
	v_and_b32_e32 v81, 0xffff0000, v146
	v_mul_f32_e32 v86, 0xbfb8aa3b, v80
	v_mul_f32_e32 v87, 0xbfb8aa3b, v81
	v_exp_f32_e32 v86, v86
	v_exp_f32_e32 v87, v87
	v_rcp_f32_e32 v52, v82
	s_nop 0
	v_pk_mul_f32 v[52:53], v[52:53], v[66:67]
	v_pk_add_f32 v[82:83], v[86:87], 1.0 op_sel_hi:[1,0]
	s_nop 0
	s_nop 0
	v_rcp_f32_e32 v51, v83
	v_lshlrev_b32_e32 v66, 16, v145
	v_and_b32_e32 v67, 0xffff0000, v145
	v_mul_f32_e32 v78, 0xbfb8aa3b, v66
	v_mul_f32_e32 v79, 0xbfb8aa3b, v67
	v_exp_f32_e32 v78, v78
	v_exp_f32_e32 v79, v79
	v_rcp_f32_e32 v50, v82
	s_nop 0
	v_pk_mul_f32 v[50:51], v[50:51], v[80:81]
	v_pk_add_f32 v[78:79], v[78:79], 1.0 op_sel_hi:[1,0]
	s_nop 0
	s_nop 0
	v_rcp_f32_e32 v37, v79
	v_lshlrev_b32_e32 v64, 16, v144
	v_and_b32_e32 v65, 0xffff0000, v144
	v_mul_f32_e32 v80, 0xbfb8aa3b, v64
	v_mul_f32_e32 v81, 0xbfb8aa3b, v65
	v_exp_f32_e32 v80, v80
	v_exp_f32_e32 v81, v81
	v_rcp_f32_e32 v36, v78
	s_nop 0
	v_pk_mul_f32 v[36:37], v[36:37], v[66:67]
	v_pk_add_f32 v[66:67], v[80:81], 1.0 op_sel_hi:[1,0]
	v_pk_add_f32 v[78:79], v[4:5], v[20:21]
	s_nop 0
	v_pk_add_f32 v[62:63], v[2:3], v[18:19]
	v_rcp_f32_e32 v35, v67
	v_add_f32_e32 v34, 0, v62
	v_add_f32_e32 v34, v63, v34
	v_add_f32_e32 v34, v78, v34
	v_add_f32_e32 v34, v79, v34
	v_add_f32_e32 v34, v84, v34
	v_add_f32_e32 v34, v85, v34
	v_add_f32_e32 v34, v68, v34
	v_add_f32_e32 v34, v69, v34
	v_add_f32_e32 v34, v70, v34
	v_add_f32_e32 v34, v71, v34
	v_add_f32_e32 v34, v72, v34
	v_add_f32_e32 v34, v73, v34
	v_add_f32_e32 v34, v74, v34
	v_add_f32_e32 v34, v75, v34
	v_add_f32_e32 v34, v76, v34
	v_add_f32_e32 v34, v77, v34
	ds_bpermute_b32 v62, v131, v34
	s_mov_b32 s4, 0x800000
	s_waitcnt lgkmcnt(0)
	v_add_f32_e32 v34, v34, v62
	v_mul_f32_e32 v34, 0x3c800000, v34
	v_pk_add_f32 v[18:19], v[18:19], v[34:35] op_sel_hi:[1,0] neg_lo:[0,1] neg_hi:[0,1]
	v_pk_add_f32 v[2:3], v[2:3], v[34:35] op_sel_hi:[1,0] neg_lo:[0,1] neg_hi:[0,1]
	v_pk_mul_f32 v[62:63], v[18:19], v[18:19]
	v_pk_add_f32 v[20:21], v[20:21], v[34:35] op_sel_hi:[1,0] neg_lo:[0,1] neg_hi:[0,1]
	v_pk_fma_f32 v[62:63], v[2:3], v[2:3], v[62:63]
	v_pk_add_f32 v[4:5], v[4:5], v[34:35] op_sel_hi:[1,0] neg_lo:[0,1] neg_hi:[0,1]
	v_pk_mul_f32 v[68:69], v[20:21], v[20:21]
	v_pk_add_f32 v[38:39], v[38:39], v[34:35] op_sel_hi:[1,0] neg_lo:[0,1] neg_hi:[0,1]
	v_pk_fma_f32 v[68:69], v[4:5], v[4:5], v[68:69]
	v_pk_add_f32 v[54:55], v[54:55], v[34:35] op_sel_hi:[1,0] neg_lo:[0,1] neg_hi:[0,1]
	v_pk_add_f32 v[40:41], v[40:41], v[34:35] op_sel_hi:[1,0] neg_lo:[0,1] neg_hi:[0,1]
	v_pk_add_f32 v[56:57], v[56:57], v[34:35] op_sel_hi:[1,0] neg_lo:[0,1] neg_hi:[0,1]
	v_pk_add_f32 v[42:43], v[42:43], v[34:35] op_sel_hi:[1,0] neg_lo:[0,1] neg_hi:[0,1]
	v_pk_add_f32 v[58:59], v[58:59], v[34:35] op_sel_hi:[1,0] neg_lo:[0,1] neg_hi:[0,1]
	v_pk_add_f32 v[44:45], v[44:45], v[34:35] op_sel_hi:[1,0] neg_lo:[0,1] neg_hi:[0,1]
	v_pk_add_f32 v[60:61], v[60:61], v[34:35] op_sel_hi:[1,0] neg_lo:[0,1] neg_hi:[0,1]
	v_pk_add_f32 v[46:47], v[46:47], v[34:35] op_sel_hi:[1,0] neg_lo:[0,1] neg_hi:[0,1]
	v_pk_add_f32 v[78:79], v[90:91], v[34:35] op_sel_hi:[1,0] neg_lo:[0,1] neg_hi:[0,1]
	v_pk_add_f32 v[48:49], v[48:49], v[34:35] op_sel_hi:[1,0] neg_lo:[0,1] neg_hi:[0,1]
	v_pk_add_f32 v[32:33], v[32:33], v[34:35] op_sel_hi:[1,0] neg_lo:[0,1] neg_hi:[0,1]
	v_add_f32_e32 v34, v62, v63
	v_pk_mul_f32 v[70:71], v[54:55], v[54:55]
	v_add_f32_e32 v34, v68, v34
	v_pk_fma_f32 v[70:71], v[38:39], v[38:39], v[70:71]
	v_add_f32_e32 v34, v69, v34
	v_pk_mul_f32 v[72:73], v[56:57], v[56:57]
	v_add_f32_e32 v34, v70, v34
	v_pk_fma_f32 v[72:73], v[40:41], v[40:41], v[72:73]
	v_add_f32_e32 v34, v71, v34
	v_pk_mul_f32 v[74:75], v[58:59], v[58:59]
	v_add_f32_e32 v34, v72, v34
	v_pk_fma_f32 v[74:75], v[42:43], v[42:43], v[74:75]
	v_add_f32_e32 v34, v73, v34
	v_pk_mul_f32 v[76:77], v[60:61], v[60:61]
	v_add_f32_e32 v34, v74, v34
	v_pk_fma_f32 v[76:77], v[44:45], v[44:45], v[76:77]
	v_add_f32_e32 v34, v75, v34
	v_pk_mul_f32 v[80:81], v[78:79], v[78:79]
	v_add_f32_e32 v34, v76, v34
	v_pk_fma_f32 v[80:81], v[46:47], v[46:47], v[80:81]
	v_add_f32_e32 v34, v77, v34
	v_pk_mul_f32 v[82:83], v[32:33], v[32:33]
	v_add_f32_e32 v34, v80, v34
	v_pk_fma_f32 v[82:83], v[48:49], v[48:49], v[82:83]
	v_add_f32_e32 v34, v81, v34
	v_add_f32_e32 v34, v82, v34
	v_add_f32_e32 v34, v83, v34
	ds_bpermute_b32 v62, v131, v34
	s_waitcnt lgkmcnt(0)
; __device__ __forceinline__ float siluf_(float x) { return x * sigmoidf_(x); }
; __device__ __forceinline__ unsigned pk2n(float lo, float hi) { return __builtin_bit_cast(unsigned, __builtin_convertvector((f32v2_t){lo, hi}, bf16v2_t)); }
; __device__ __forceinline__ void ph_ret_chunk(unsigned char* lds_, bf16_t* Z, const bf16_t* KVF, const bf16_t* KVB, const float* decay_logit, const float* gn_w, int with_ctx, int u0, int ustep, unsigned* kvc, unsigned* barw) { PH_IDS;
;     ...
;         const float rstd = rsqrtf(s2 * (1.f / 64) + EPS);
;         u32x2 wv[2][4];
; #pragma unroll
;         for (int g = 0; g < 4; ++g)
; #pragma unroll
;             for (int blk = 0; blk < 2; ++blk) {
;                 const int d = blk * 32 + 8 * g + 4 * hi;
;                 const u32x2 gt = gtv[2 * g + blk];
;                 const f32x4 gw = gwv[2 * g + blk];
;                 float y[4];
; #pragma unroll
;                 for (int q = 0; q < 4; ++q) { const float ov = blk ? o1[4 * g + q] : o0[4 * g + q]; const unsigned gb = q < 2 ? gt.x : gt.y; const float gv = __uint_as_float((q & 1) ? (gb & 0xffff0000u) : (gb << 16));
;                     y[q] = siluf_(gv) * ((ov - mu) * rstd * gw[q]); }
;                 wv[blk][g].x = pk2n(y[0], y[1]); wv[blk][g].y = pk2n(y[2], y[3]);
;             }
; #pragma unroll
;         for (int blk = 0; blk < 2; ++blk)
; #pragma unroll
;             for (int g = 0; g < 4; g += 2) {
;                 auto rx = __builtin_amdgcn_permlane32_swap(wv[blk][g].x, wv[blk][g + 1].x, false, false), ry = __builtin_amdgcn_permlane32_swap(wv[blk][g].y, wv[blk][g + 1].y, false, false);
;                 *(u32x4*)(zq + C_RQ + h * 64 + blk * 32 + 8 * g + 8 * hi) = (u32x4){(unsigned)rx[0], (unsigned)ry[0], (unsigned)rx[1], (unsigned)ry[1]};
;             }
	v_add_f32_e32 v34, v34, v62
	v_fmamk_f32 v34, v34, 0x3c800000, v207
	v_mul_f32_e32 v62, 0x4b800000, v34
	v_cmp_gt_f32_e64 s[4:5], s4, v34
	v_cndmask_b32_e64 v34, v34, v62, s[4:5]
	v_rsq_f32_e32 v62, v34
	v_rcp_f32_e32 v34, v66
	s_nop 0
	v_pk_mul_f32 v[34:35], v[34:35], v[64:65]
	v_mul_f32_e32 v63, 0x45800000, v62
	v_cndmask_b32_e64 v62, v62, v63, s[4:5]
	v_pk_mul_f32 v[2:3], v[2:3], v[62:63] op_sel_hi:[1,0]
	v_pk_mul_f32 v[4:5], v[4:5], v[62:63] op_sel_hi:[1,0]
	v_pk_mul_f32 v[2:3], v[122:123], v[2:3]
	v_pk_mul_f32 v[4:5], v[124:125], v[4:5]
	v_pk_mul_f32 v[2:3], v[34:35], v[2:3]
	v_pk_mul_f32 v[4:5], v[36:37], v[4:5]
	v_cvt_pk_bf16_f32 v2, v2, v3
	v_cvt_pk_bf16_f32 v3, v4, v5
	v_pk_mul_f32 v[4:5], v[18:19], v[62:63] op_sel_hi:[1,0]
	v_pk_mul_f32 v[18:19], v[20:21], v[62:63] op_sel_hi:[1,0]
	v_pk_mul_f32 v[4:5], v[118:119], v[4:5]
	v_pk_mul_f32 v[18:19], v[120:121], v[18:19]
	v_pk_mul_f32 v[4:5], v[50:51], v[4:5]
	v_pk_mul_f32 v[20:21], v[52:53], v[18:19]
	v_cvt_pk_bf16_f32 v18, v4, v5
	v_pk_mul_f32 v[4:5], v[38:39], v[62:63] op_sel_hi:[1,0]
	v_cvt_pk_bf16_f32 v19, v20, v21
	v_pk_mul_f32 v[4:5], v[114:115], v[4:5]
	s_nop 0
	v_pk_mul_f32 v[4:5], v[6:7], v[4:5]
	v_pk_mul_f32 v[6:7], v[40:41], v[62:63] op_sel_hi:[1,0]
	v_cvt_pk_bf16_f32 v4, v4, v5
	v_pk_mul_f32 v[6:7], v[116:117], v[6:7]
	s_nop 0
	v_permlane32_swap_b32_e32 v2, v4
	v_pk_mul_f32 v[6:7], v[8:9], v[6:7]
	v_pk_mul_f32 v[8:9], v[56:57], v[62:63] op_sel_hi:[1,0]
	v_cvt_pk_bf16_f32 v5, v6, v7
	v_pk_mul_f32 v[6:7], v[54:55], v[62:63] op_sel_hi:[1,0]
	v_pk_mul_f32 v[8:9], v[112:113], v[8:9]
	v_pk_mul_f32 v[6:7], v[110:111], v[6:7]
	v_pk_mul_f32 v[8:9], v[24:25], v[8:9]
	v_pk_mul_f32 v[6:7], v[22:23], v[6:7]
	v_cvt_pk_bf16_f32 v21, v8, v9
	v_cvt_pk_bf16_f32 v20, v6, v7
	v_pk_mul_f32 v[6:7], v[42:43], v[62:63] op_sel_hi:[1,0]
	v_pk_mul_f32 v[8:9], v[44:45], v[62:63] op_sel_hi:[1,0]
	v_pk_mul_f32 v[6:7], v[106:107], v[6:7]
	v_pk_mul_f32 v[8:9], v[108:109], v[8:9]
	v_pk_mul_f32 v[6:7], v[10:11], v[6:7]
	v_pk_mul_f32 v[8:9], v[12:13], v[8:9]
	v_cvt_pk_bf16_f32 v6, v6, v7
	v_cvt_pk_bf16_f32 v7, v8, v9
	v_pk_mul_f32 v[8:9], v[58:59], v[62:63] op_sel_hi:[1,0]
	v_pk_mul_f32 v[10:11], v[60:61], v[62:63] op_sel_hi:[1,0]
	s_waitcnt vmcnt(1)
	v_pk_mul_f32 v[8:9], v[102:103], v[8:9]
	v_pk_mul_f32 v[10:11], v[104:105], v[10:11]
	v_pk_mul_f32 v[8:9], v[26:27], v[8:9]
	v_pk_mul_f32 v[12:13], v[28:29], v[10:11]
	v_cvt_pk_bf16_f32 v10, v8, v9
	v_pk_mul_f32 v[8:9], v[46:47], v[62:63] op_sel_hi:[1,0]
	v_cvt_pk_bf16_f32 v11, v12, v13
	v_pk_mul_f32 v[8:9], v[98:99], v[8:9]
	v_pk_mul_f32 v[12:13], v[48:49], v[62:63] op_sel_hi:[1,0]
	v_pk_mul_f32 v[8:9], v[14:15], v[8:9]
	v_lshlrev_b32_e32 v14, 16, v143
	v_and_b32_e32 v15, 0xffff0000, v143
	v_mul_f32_e32 v22, 0xbfb8aa3b, v14
	v_mul_f32_e32 v23, 0xbfb8aa3b, v15
	v_exp_f32_e32 v22, v22
	v_exp_f32_e32 v23, v23
	v_pk_mul_f32 v[12:13], v[100:101], v[12:13]
	v_cvt_pk_bf16_f32 v8, v8, v9
	v_pk_mul_f32 v[12:13], v[16:17], v[12:13]
	v_pk_mul_f32 v[16:17], v[78:79], v[62:63] op_sel_hi:[1,0]
	v_cvt_pk_bf16_f32 v9, v12, v13
	v_pk_add_f32 v[12:13], v[22:23], 1.0 op_sel_hi:[1,0]
	s_waitcnt vmcnt(0)
	v_pk_mul_f32 v[16:17], v[94:95], v[16:17]
	v_pk_mul_f32 v[16:17], v[30:31], v[16:17]
	v_permlane32_swap_b32_e32 v3, v5
	v_rcp_f32_e32 v13, v13
	v_permlane32_swap_b32_e32 v6, v8
	v_rcp_f32_e32 v12, v12
	s_nop 0
	v_pk_mul_f32 v[12:13], v[12:13], v[14:15]
	v_pk_mul_f32 v[14:15], v[32:33], v[62:63] op_sel_hi:[1,0]
	v_permlane32_swap_b32_e32 v7, v9
	v_pk_mul_f32 v[14:15], v[96:97], v[14:15]
	v_permlane32_swap_b32_e32 v18, v20
	v_pk_mul_f32 v[14:15], v[12:13], v[14:15]
	v_cvt_pk_bf16_f32 v12, v16, v17
	v_cvt_pk_bf16_f32 v13, v14, v15
	v_permlane32_swap_b32_e32 v19, v21
	v_permlane32_swap_b32_e32 v10, v12
	v_permlane32_swap_b32_e32 v11, v13
	global_store_dwordx4 v[140:141], v[2:5], off offset:2880
	global_store_dwordx4 v[140:141], v[6:9], off offset:2912
	global_store_dwordx4 v[140:141], v[18:21], off offset:2944
	global_store_dwordx4 v[140:141], v[10:13], off offset:2976
	s_barrier
	s_mov_b64 s[4:5], 0
; #define IN(i) (kargs()->in[i])
; #define WSB(T, off) ((T*)(kargs()->ws + (off)))
; #define OSB(T, off) ((T*)((unsigned char*)kargs()->out + (off)))
; __device__ __forceinline__ void ph_ret_chunk(unsigned char* lds_, bf16_t* Z, const bf16_t* KVF, const bf16_t* KVB, const float* decay_logit, const float* gn_w, int with_ctx, int u0, int ustep, unsigned* kvc, unsigned* barw) { PH_IDS;
;     ...
;     for (int u = u0; u < nunits; u += ustep) {
;         const bool lat = u < 256; const int bh = lat ? (u >> 3) : (u - 256), qb = lat ? (u & 7) : 0, b = bh >> 2, h = bh & 3;
;         const float lgf = -log1pf(__expf(-decay_logit[h])) * 1.4426950408889634f, lgb = -log1pf(__expf(-decay_logit[4 + h])) * 1.4426950408889634f;
;         const int qw0 = qb * 256 + wid * 32, qpos = qw0 + r32;
;         const int qrow = (lat ? b * 2048 : RL + b * 256) + qpos;
;         bf16_t* zq = Z + (size_t)qrow * ZW;
;         u32x4 sK[4], sV[4]; bf16x8 qf[4];
;         { const size_t rb = (lat ? (size_t)b * 2048 + qb * 256 : (size_t)RL + b * 256);
; #pragma unroll
;           for (int j = 0; j < 4; ++j) { const bf16_t* zr = Z + (rb + 64 * j + prow) * ZW + h * 64 + pc * 8; sK[j] = *(const u32x4*)(zr + C_RK); sV[j] = *(const u32x4*)(zr + C_RV); } }
; #pragma unroll
;         for (int st = 0; st < 4; ++st) qf[st] = *(const bf16x8*)(zq + C_RQ + h * 64 + 16 * st + 8 * hi);
;         if (kvc != nullptr && tid_ == 0) dep_spin(kvc, (unsigned)G_, barw);
; template <int L> __device__ __forceinline__ void layer_body(unsigned char* lds, XcdBarrier& bar) {
;     ...
;                 if (q >= Q_END) break;
;                 if (q < Q_ATTC) ph_attn_mfma(lds, QP, KP, VP, ZP, WCTX, q - Q_ATT, 1 << 20);
;                 else if (q < Q_S5) ph_attn_mfma(lds, QP, KP, VP, ZP, WCTX, 256 + q - Q_ATTC, 1 << 20);
;                 else if (q < Q_RET) ph_s5_out(lds, ZP, OSB(bf16_t, OS_TZB), OSB(bf16_t, OS_CQ), WSB(float2, WS_LP), OSB(float, OS_SLOC), WSB(float, WS_LAMT), ZP, LASTL ? 16 : 18, q - Q_S5, 1 << 20);
;                 else if (q < Q_RETC) ph_ret_chunk(lds, ZP, WSB(bf16_t, WS_KVF), OSB(bf16_t, OS_KVB), IN(I_RDEC) + l * 8, IN(I_RGN) + l * 256, WCTX, q - Q_RET, 1 << 20, kvc_, WSB(unsigned, WS_BAR));
.LBB0_765:
	s_and_b64 vcc, exec, s[4:5]
	s_cbranch_vccz .LBB0_776
	s_mov_b64 s[4:5], s[0:1]
	s_load_dwordx2 s[6:7], s[4:5], 0xf8
	s_mov_b64 s[4:5], s[0:1]
	s_mov_b64 s[8:9], s[0:1]
	s_load_dwordx2 s[4:5], s[4:5], 0xf8
	s_waitcnt lgkmcnt(0)
	s_add_u32 s12, s6, 0x4c00000
	s_addc_u32 s13, s7, 0
	s_load_dwordx2 s[6:7], s[8:9], 0xf0
	s_mov_b64 s[8:9], s[0:1]
	s_mov_b64 s[10:11], s[0:1]
	s_load_dwordx2 s[8:9], s[8:9], 0xc0
	s_load_dwordx2 s[20:21], s[10:11], 0xc8
	s_mov_b64 s[10:11], s[0:1]
	v_mov_b32_e32 v123, v0
	s_mov_b32 s14, s2
	s_add_i32 s18, s50, 0xfffffdc0
	v_readfirstlane_b32 s39, v123
	s_ashr_i32 s14, s39, 1
	v_mov_b32_e32 v2, s14
	s_and_b32 s43, s50, 7
	s_bfe_u32 s19, s18, 0x20003
	s_waitcnt vmcnt(7)
	v_bfi_b32 v160, s67, v2, v123
	s_lshl_b32 s14, s19, 2
	s_lshl_b32 s38, s43, 8
	s_mov_b32 s22, s3
	s_lshr_b32 s56, s18, 5
	v_mov_b32_e32 v4, s14
	v_add_u32_e32 v131, s38, v160
	s_waitcnt lgkmcnt(0)
	global_load_dword v48, v4, s[8:9]
	global_load_dword v47, v4, s[8:9] offset:16
	v_lshl_add_u32 v4, s56, 11, v131
	v_ashrrev_i32_e32 v38, 3, v123
	v_and_b32_e32 v46, 7, v123
	v_ashrrev_i32_e32 v5, 31, v4
	s_lshl_b64 s[8:9], s[56:57], 11
	v_ashrrev_i32_e32 v39, 31, v38
	v_lshlrev_b32_e32 v86, 4, v46
	v_mov_b32_e32 v87, v130
	v_lshlrev_b64 v[4:5], 12, v[4:5]
	s_or_b32 s8, s8, s38
	v_lshl_add_u64 v[2:3], s[12:13], 0, v[86:87]
	v_lshl_add_u64 v[34:35], s[12:13], 0, v[4:5]
	v_lshl_add_u64 v[4:5], s[8:9], 0, v[38:39]
	s_lshl_b32 s56, s19, 7
	v_lshl_add_u64 v[2:3], v[2:3], 0, s[56:57]
	v_lshlrev_b64 v[4:5], 12, v[4:5]
	v_lshl_add_u64 v[26:27], v[2:3], 0, v[4:5]
	v_add_co_u32_e32 v14, vcc, s48, v26
	v_bfe_u32 v122, v123, 5, 1
	s_nop 0
	v_addc_co_u32_e32 v15, vcc, 0, v27, vcc
	v_add_co_u32_e32 v22, vcc, s49, v26
	v_lshl_add_u64 v[80:81], v[34:35], 0, s[56:57]
	s_nop 0
	v_addc_co_u32_e32 v23, vcc, 0, v27, vcc
	v_add_co_u32_e32 v30, vcc, 0xc0000, v26
	v_lshlrev_b32_e32 v78, 4, v122
	v_mov_b32_e32 v79, v130
	v_addc_co_u32_e32 v31, vcc, 0, v27, vcc
	v_lshl_add_u64 v[140:141], v[80:81], 0, v[78:79]
	global_load_dwordx4 v[6:9], v[26:27], off offset:832
	global_load_dwordx4 v[2:5], v[26:27], off offset:1344
	global_load_dwordx4 v[10:13], v[14:15], off offset:832
	s_nop 0
	global_load_dwordx4 v[14:17], v[14:15], off offset:1344
	s_nop 0
	global_load_dwordx4 v[18:21], v[22:23], off offset:832
	s_nop 0
	global_load_dwordx4 v[22:25], v[22:23], off offset:1344
	s_nop 0
	global_load_dwordx4 v[26:29], v[30:31], off offset:832
	s_nop 0
	global_load_dwordx4 v[30:33], v[30:31], off offset:1344
	s_nop 0
	global_load_dwordx4 v[66:69], v[140:141], off offset:2880
	global_load_dwordx4 v[102:105], v[140:141], off offset:2912
	global_load_dwordx4 v[98:101], v[140:141], off offset:2944
	global_load_dwordx4 v[94:97], v[140:141], off offset:2976
	s_cmp_lg_u32 s100, 0
	s_cbranch_scc1 .Lkvc_skip_b
	v_cmp_eq_u32_e32 vcc, 0, v123
	s_and_saveexec_b64 s[8:9], vcc
	s_cbranch_execz .LBB0_1098
	s_load_dwordx2 s[10:11], s[10:11], 0xf8
	global_load_dword v34, v130, s[52:53] sc1
	s_waitcnt vmcnt(0)
	v_cmp_le_u32_e32 vcc, s22, v34
	s_cbranch_vccnz .LBB0_1097
	s_waitcnt lgkmcnt(0)
	s_add_u32 s10, s10, 0xc0200
	s_addc_u32 s11, s11, 0
	s_mov_b32 s23, 1
	s_branch .LBB0_770

; #define LAS __attribute__((address_space(3)))
; #define ST_PUT(k) (*(LAS u32x4*)(sto + (k) * ST_SZ) = pack8(sa, sb))
; #define ST_PUTB(k) (*(LAS u32x4*)(sto + (k) * ST_SZ) = pack8(sc, sd))
; __device__ __forceinline__ void ph_ret_chunk(unsigned char* lds_, bf16_t* Z, const bf16_t* KVF, const bf16_t* KVB, const float* decay_logit, const float* gn_w, int with_ctx, int u0, int ustep, unsigned* kvc, unsigned* barw) { PH_IDS;
;     ...
;         if (kvc != nullptr && tid_ == 0) dep_spin(kvc, (unsigned)G_, barw);
;         __syncthreads();
; #pragma unroll
;         for (int j = 0; j < 4; ++j) { *(LAS u32x4*)(sm + j * BUF_R + koff) = sK[j]; *(LAS u32x4*)(sm + j * BUF_R + voff) = sV[j]; }
;         {
;             const float g128f = __builtin_amdgcn_exp2f(lgf * 128.f), g128b = __builtin_amdgcn_exp2f(lgb * 128.f);
;             const bf16_t* kf = KVF + (size_t)bh * 18 * 4096 + tid_ * 8; const bf16_t* kb = KVB + (size_t)bh * 18 * 4096 + tid_ * 8;
;             LAS char* sto = sm + ST_OFF + (tid_ >> 3) * KP_R + (tid_ & 7) * 16;
;             f32x4 sa = (f32x4){0.f, 0.f, 0.f, 0.f}, sb = sa, ta, tb;
;     ...
;             if (lat) {
;                 const int cA = 2 * qb, n1 = 2 + cA, nb = 16 - cA;
;                 u32x4 Lq[9], Lr[9]; f32x4 sc = (f32x4){0.f, 0.f, 0.f, 0.f}, sd = sc;
;     ...
; #pragma unroll
;                 for (int hf = 0; hf < 2; ++hf) {
; #pragma unroll
;                     for (int k = 0; k < 9; ++k) { const int kk = 9 * hf + k;
;                         if (kk <= n1 && kk < 17) Lq[k] = *(const u32x4*)(kf + (size_t)kk * 4096);
;                         if (kk <= nb && kk < 17) Lr[k] = *(const u32x4*)(kb + (size_t)(kk == 0 ? 1 : (kk == 1 ? 0 : 19 - kk)) * 4096); }
; #pragma unroll
;                     for (int k = 0; k < 9; ++k) { const int kk = 9 * hf + k;
;                         if (kk == n1) ST_PUT(0); if (kk <= n1 && kk < 17) { unpack8(Lq[k], ta, tb); sa = sa * g128f + ta; sb = sb * g128f + tb; }
;                         if (kk == nb) ST_PUTB(3); if (kk <= nb && kk < 17) { unpack8(Lr[k], ta, tb); sc = sc * g128b + ta; sd = sd * g128b + tb; } }
.LBB0_1098:
	s_or_b64 exec, exec, s[8:9]
	s_mov_b32 s100, 1
.Lkvc_skip_b:
	v_lshlrev_b32_e32 v82, 3, v123
	s_lshr_b32 s8, s18, 3
	v_ashrrev_i32_e32 v83, 31, v82
	v_lshlrev_b64 v[34:35], 1, v[82:83]
	s_mul_i32 s56, s8, 0x12000
	v_lshl_add_u64 v[36:37], s[4:5], 0, v[34:35]
	v_lshl_add_u64 v[34:35], s[6:7], 0, v[34:35]
	s_lshl_b64 s[4:5], s[56:57], 1
	v_lshl_add_u64 v[70:71], v[36:37], 0, s[4:5]
	v_lshl_add_u64 v[40:41], v[34:35], 0, s[4:5]
	s_mov_b32 s4, 0x380000
	v_add_co_u32_e32 v34, vcc, s4, v70
	s_mov_b32 s4, 0x1602000
	s_nop 0
	v_addc_co_u32_e32 v35, vcc, 0, v71, vcc
	s_barrier
	global_load_dwordx4 v[62:65], v[34:35], off
	v_add_co_u32_e32 v34, vcc, s4, v40
	s_mov_b32 s4, 0x382000
	s_nop 0
	v_addc_co_u32_e32 v35, vcc, 0, v41, vcc
	global_load_dwordx4 v[58:61], v[34:35], off
	v_add_co_u32_e32 v34, vcc, s4, v70
	s_mov_b32 s4, 0x1600000
	s_nop 0
	v_addc_co_u32_e32 v35, vcc, 0, v71, vcc
	global_load_dwordx4 v[54:57], v[34:35], off
	v_add_co_u32_e32 v34, vcc, s4, v40
	v_lshlrev_b32_e32 v39, 10, v46
	s_nop 0
	v_addc_co_u32_e32 v35, vcc, 0, v41, vcc
	global_load_dwordx4 v[50:53], v[34:35], off
	v_add_co_u32_e32 v34, vcc, 0x384000, v70
	s_waitcnt vmcnt(17)
	v_mul_f32_e32 v46, 0xbfb8aa3b, v48
	v_addc_co_u32_e32 v35, vcc, 0, v71, vcc
	global_load_dwordx4 v[42:45], v[34:35], off
	v_add_co_u32_e32 v34, vcc, 0x1622000, v40
	v_exp_f32_e32 v84, v46
	s_nop 0
	v_addc_co_u32_e32 v35, vcc, 0, v41, vcc
	global_load_dwordx4 v[34:37], v[34:35], off
	s_waitcnt vmcnt(18)
	v_mul_f32_e32 v47, 0xbfb8aa3b, v47
	v_exp_f32_e32 v87, v47
	s_movk_i32 s4, 0x90
	v_add_f32_e32 v89, 1.0, v84
	v_mul_lo_u32 v85, v38, s4
	v_frexp_mant_f32_e32 v47, v89
	s_mov_b32 s4, 0x3f2aaaab
	v_add_f32_e32 v88, 1.0, v87
	s_lshl_b32 s42, s19, 6
	v_cmp_gt_f32_e64 s[6:7], s4, v47
	v_frexp_mant_f32_e32 v47, v88
	v_and_b32_e32 v39, 0x1000, v39
	v_lshlrev_b32_e32 v83, 4, v123
	v_cmp_gt_f32_e64 s[4:5], s4, v47
	v_add3_u32 v47, 0, v85, v86
	s_cmp_eq_u32 s43, 0
	v_lshlrev_b32_e32 v38, 6, v38
	v_and_b32_e32 v46, 48, v83
	s_waitcnt vmcnt(17)
	ds_write_b128 v47, v[6:9]
	v_add_u32_e32 v6, 0, v39
	s_mov_b64 s[8:9], 0x380000
	s_cselect_b64 s[34:35], -1, 0
	s_cmp_lg_u32 s43, 0
	v_and_b32_e32 v79, 31, v123
	v_add3_u32 v6, v6, v38, v46
	v_lshl_add_u64 v[116:117], v[70:71], 0, s[8:9]
	s_cselect_b64 s[8:9], -1, 0
	s_and_b64 vcc, exec, s[34:35]
	s_waitcnt vmcnt(16)
	ds_write_b128 v6, v[2:5] offset:9216
	s_waitcnt vmcnt(15)
	ds_write_b128 v47, v[10:13] offset:17408
	s_waitcnt vmcnt(14)
	ds_write_b128 v6, v[14:17] offset:26624
	s_waitcnt vmcnt(13)
	ds_write_b128 v47, v[18:21] offset:34816
	s_waitcnt vmcnt(12)
	ds_write_b128 v6, v[22:25] offset:44032
	s_waitcnt vmcnt(11)
	ds_write_b128 v47, v[26:29] offset:52224
	s_waitcnt vmcnt(10)
	ds_write_b128 v6, v[30:33] offset:61440
	s_cbranch_vccnz .LBB0_1100
	v_add_co_u32_e32 v2, vcc, 0x6000, v116
	s_nop 1
	v_addc_co_u32_e32 v3, vcc, 0, v117, vcc
	global_load_dwordx4 v[46:49], v[2:3], off

; #define IN(i) (kargs()->in[i])
; #define WSB(T, off) ((T*)(kargs()->ws + (off)))
; #define OSB(T, off) ((T*)((unsigned char*)kargs()->out + (off)))
; __device__ __forceinline__ void ph_ret_chunk(unsigned char* lds_, bf16_t* Z, const bf16_t* KVF, const bf16_t* KVB, const float* decay_logit, const float* gn_w, int with_ctx, int u0, int ustep, unsigned* kvc, unsigned* barw) { PH_IDS;
;     ...
;     for (int u = u0; u < nunits; u += ustep) {
;         const bool lat = u < 256; const int bh = lat ? (u >> 3) : (u - 256), qb = lat ? (u & 7) : 0, b = bh >> 2, h = bh & 3;
;         const float lgf = -log1pf(__expf(-decay_logit[h])) * 1.4426950408889634f, lgb = -log1pf(__expf(-decay_logit[4 + h])) * 1.4426950408889634f;
;         const int qw0 = qb * 256 + wid * 32, qpos = qw0 + r32;
;         const int qrow = (lat ? b * 2048 : RL + b * 256) + qpos;
;         bf16_t* zq = Z + (size_t)qrow * ZW;
;         u32x4 sK[4], sV[4]; bf16x8 qf[4];
;         { const size_t rb = (lat ? (size_t)b * 2048 + qb * 256 : (size_t)RL + b * 256);
; #pragma unroll
;           for (int j = 0; j < 4; ++j) { const bf16_t* zr = Z + (rb + 64 * j + prow) * ZW + h * 64 + pc * 8; sK[j] = *(const u32x4*)(zr + C_RK); sV[j] = *(const u32x4*)(zr + C_RV); } }
; #pragma unroll
;         for (int st = 0; st < 4; ++st) qf[st] = *(const bf16x8*)(zq + C_RQ + h * 64 + 16 * st + 8 * hi);
;         if (kvc != nullptr && tid_ == 0) dep_spin(kvc, (unsigned)G_, barw);
; template <int L> __device__ __forceinline__ void layer_body(unsigned char* lds, XcdBarrier& bar) {
;     ...
;                 else if (q < Q_RETC) ph_ret_chunk(lds, ZP, WSB(bf16_t, WS_KVF), OSB(bf16_t, OS_KVB), IN(I_RDEC) + l * 8, IN(I_RGN) + l * 256, WCTX, q - Q_RET, 1 << 20, kvc_, WSB(unsigned, WS_BAR));
.LBB0_2571:
	s_cmpk_gt_i32 s89, 0xff
	s_cbranch_scc0 .LBB0_2959
	s_and_b64 vcc, exec, s[4:5]
	s_cbranch_vccz .LBB0_2731
	s_mov_b64 s[4:5], s[0:1]
	s_load_dwordx2 s[6:7], s[4:5], 0xf8
	s_mov_b64 s[4:5], s[0:1]
	s_mov_b64 s[8:9], s[0:1]
	s_load_dwordx2 s[4:5], s[4:5], 0xf8
	s_waitcnt lgkmcnt(0)
	s_add_u32 s12, s6, 0x4c00000
	s_addc_u32 s13, s7, 0
	s_load_dwordx2 s[6:7], s[8:9], 0xf0
	s_mov_b64 s[8:9], s[0:1]
	s_mov_b64 s[10:11], s[0:1]
	s_load_dwordx2 s[8:9], s[8:9], 0xc0
	s_load_dwordx2 s[20:21], s[10:11], 0xc8
	s_mov_b64 s[10:11], s[0:1]
	v_mov_b32_e32 v123, v0
	s_mov_b32 s14, s2
	s_add_i32 s18, s89, 0xfffffe00
	v_readfirstlane_b32 s42, v123
	s_ashr_i32 s14, s42, 1
	v_mov_b32_e32 v2, s14
	s_and_b32 s43, s89, 7
	s_bfe_u32 s19, s18, 0x20003
	s_waitcnt vmcnt(7)
	v_bfi_b32 v160, s59, v2, v123
	s_lshl_b32 s14, s19, 2
	s_lshl_b32 s38, s43, 8
	s_mov_b32 s22, s3
	s_lshr_b32 s54, s18, 5
	v_mov_b32_e32 v4, s14
	v_add_u32_e32 v131, s38, v160
	s_waitcnt lgkmcnt(0)
	global_load_dword v48, v4, s[8:9] offset:32
	global_load_dword v47, v4, s[8:9] offset:48
	v_lshl_add_u32 v4, s54, 11, v131
	v_ashrrev_i32_e32 v38, 3, v123
	v_and_b32_e32 v46, 7, v123
	v_ashrrev_i32_e32 v5, 31, v4
	s_lshl_b64 s[8:9], s[54:55], 11
	v_ashrrev_i32_e32 v39, 31, v38
	v_lshlrev_b32_e32 v86, 4, v46
	v_mov_b32_e32 v87, v130
	v_lshlrev_b64 v[4:5], 12, v[4:5]
	s_or_b32 s8, s8, s38
	v_lshl_add_u64 v[2:3], s[12:13], 0, v[86:87]
	v_lshl_add_u64 v[34:35], s[12:13], 0, v[4:5]
	v_lshl_add_u64 v[4:5], s[8:9], 0, v[38:39]
	s_lshl_b32 s54, s19, 7
	v_lshl_add_u64 v[2:3], v[2:3], 0, s[54:55]
	v_lshlrev_b64 v[4:5], 12, v[4:5]
	v_lshl_add_u64 v[26:27], v[2:3], 0, v[4:5]
	s_mov_b32 s8, 0x40000
	v_add_co_u32_e32 v14, vcc, s8, v26
	s_mov_b32 s8, 0x80000
	s_nop 0
	v_addc_co_u32_e32 v15, vcc, 0, v27, vcc
	v_add_co_u32_e32 v22, vcc, s8, v26
	v_bfe_u32 v122, v123, 5, 1
	s_nop 0
	v_addc_co_u32_e32 v23, vcc, 0, v27, vcc
	v_add_co_u32_e32 v30, vcc, 0xc0000, v26
	v_lshl_add_u64 v[80:81], v[34:35], 0, s[54:55]
	v_lshlrev_b32_e32 v78, 4, v122
	v_mov_b32_e32 v79, v130
	v_addc_co_u32_e32 v31, vcc, 0, v27, vcc
	v_lshl_add_u64 v[140:141], v[80:81], 0, v[78:79]
	global_load_dwordx4 v[6:9], v[26:27], off offset:832
	global_load_dwordx4 v[2:5], v[26:27], off offset:1344
	global_load_dwordx4 v[10:13], v[14:15], off offset:832
	s_nop 0
	global_load_dwordx4 v[14:17], v[14:15], off offset:1344
	s_nop 0
	global_load_dwordx4 v[18:21], v[22:23], off offset:832
	s_nop 0
	global_load_dwordx4 v[22:25], v[22:23], off offset:1344
	s_nop 0
	global_load_dwordx4 v[26:29], v[30:31], off offset:832
	s_nop 0
	global_load_dwordx4 v[30:33], v[30:31], off offset:1344
	s_nop 0
	global_load_dwordx4 v[66:69], v[140:141], off offset:2880
	global_load_dwordx4 v[102:105], v[140:141], off offset:2912
	global_load_dwordx4 v[98:101], v[140:141], off offset:2944
	global_load_dwordx4 v[94:97], v[140:141], off offset:2976
	s_cmp_lg_u32 s101, 0
	s_cbranch_scc1 .Lkvc_skip_c
	v_cmp_eq_u32_e32 vcc, 0, v123
	s_and_saveexec_b64 s[8:9], vcc
	s_cbranch_execz .LBB0_2588
	s_load_dwordx2 s[10:11], s[10:11], 0xf8
	global_load_dword v34, v130, s[50:51] sc1
	s_waitcnt vmcnt(0)
	v_cmp_le_u32_e32 vcc, s22, v34
	s_cbranch_vccnz .LBB0_2587
	s_waitcnt lgkmcnt(0)
	s_add_u32 s10, s10, 0xc0200
	s_addc_u32 s11, s11, 0
	s_mov_b32 s23, 1
	s_branch .LBB0_2577

; #define LAS __attribute__((address_space(3)))
; #define ST_PUT(k) (*(LAS u32x4*)(sto + (k) * ST_SZ) = pack8(sa, sb))
; #define ST_PUTB(k) (*(LAS u32x4*)(sto + (k) * ST_SZ) = pack8(sc, sd))
; __device__ __forceinline__ void ph_ret_chunk(unsigned char* lds_, bf16_t* Z, const bf16_t* KVF, const bf16_t* KVB, const float* decay_logit, const float* gn_w, int with_ctx, int u0, int ustep, unsigned* kvc, unsigned* barw) { PH_IDS;
;     ...
;         if (kvc != nullptr && tid_ == 0) dep_spin(kvc, (unsigned)G_, barw);
;         __syncthreads();
; #pragma unroll
;         for (int j = 0; j < 4; ++j) { *(LAS u32x4*)(sm + j * BUF_R + koff) = sK[j]; *(LAS u32x4*)(sm + j * BUF_R + voff) = sV[j]; }
;         {
;             const float g128f = __builtin_amdgcn_exp2f(lgf * 128.f), g128b = __builtin_amdgcn_exp2f(lgb * 128.f);
;             const bf16_t* kf = KVF + (size_t)bh * 18 * 4096 + tid_ * 8; const bf16_t* kb = KVB + (size_t)bh * 18 * 4096 + tid_ * 8;
;             LAS char* sto = sm + ST_OFF + (tid_ >> 3) * KP_R + (tid_ & 7) * 16;
;             f32x4 sa = (f32x4){0.f, 0.f, 0.f, 0.f}, sb = sa, ta, tb;
;     ...
;             if (lat) {
;                 const int cA = 2 * qb, n1 = 2 + cA, nb = 16 - cA;
;                 u32x4 Lq[9], Lr[9]; f32x4 sc = (f32x4){0.f, 0.f, 0.f, 0.f}, sd = sc;
;     ...
; #pragma unroll
;                 for (int hf = 0; hf < 2; ++hf) {
; #pragma unroll
;                     for (int k = 0; k < 9; ++k) { const int kk = 9 * hf + k;
;                         if (kk <= n1 && kk < 17) Lq[k] = *(const u32x4*)(kf + (size_t)kk * 4096);
;                         if (kk <= nb && kk < 17) Lr[k] = *(const u32x4*)(kb + (size_t)(kk == 0 ? 1 : (kk == 1 ? 0 : 19 - kk)) * 4096); }
; #pragma unroll
;                     for (int k = 0; k < 9; ++k) { const int kk = 9 * hf + k;
;                         if (kk == n1) ST_PUT(0); if (kk <= n1 && kk < 17) { unpack8(Lq[k], ta, tb); sa = sa * g128f + ta; sb = sb * g128f + tb; }
;                         if (kk == nb) ST_PUTB(3); if (kk <= nb && kk < 17) { unpack8(Lr[k], ta, tb); sc = sc * g128b + ta; sd = sd * g128b + tb; } }
.LBB0_2588:
	s_or_b64 exec, exec, s[8:9]
	s_mov_b32 s101, 1
.Lkvc_skip_c:
	v_lshlrev_b32_e32 v82, 3, v123
	s_lshr_b32 s8, s18, 3
	v_ashrrev_i32_e32 v83, 31, v82
	v_lshlrev_b64 v[34:35], 1, v[82:83]
	s_mul_i32 s54, s8, 0x12000
	v_lshl_add_u64 v[36:37], s[4:5], 0, v[34:35]
	v_lshl_add_u64 v[34:35], s[6:7], 0, v[34:35]
	s_lshl_b64 s[4:5], s[54:55], 1
	v_lshl_add_u64 v[70:71], v[36:37], 0, s[4:5]
	v_lshl_add_u64 v[40:41], v[34:35], 0, s[4:5]
	s_mov_b32 s4, 0x380000
	v_add_co_u32_e32 v34, vcc, s4, v70
	s_mov_b32 s4, 0x1602000
	s_nop 0
	v_addc_co_u32_e32 v35, vcc, 0, v71, vcc
	s_barrier
	global_load_dwordx4 v[62:65], v[34:35], off
	v_add_co_u32_e32 v34, vcc, s4, v40
	s_mov_b32 s4, 0x382000
	s_nop 0
	v_addc_co_u32_e32 v35, vcc, 0, v41, vcc
	global_load_dwordx4 v[58:61], v[34:35], off
	v_add_co_u32_e32 v34, vcc, s4, v70
	s_mov_b32 s4, 0x1600000
	s_nop 0
	v_addc_co_u32_e32 v35, vcc, 0, v71, vcc
	global_load_dwordx4 v[54:57], v[34:35], off
	v_add_co_u32_e32 v34, vcc, s4, v40
	v_lshlrev_b32_e32 v39, 10, v46
	s_nop 0
	v_addc_co_u32_e32 v35, vcc, 0, v41, vcc
	global_load_dwordx4 v[50:53], v[34:35], off
	v_add_co_u32_e32 v34, vcc, 0x384000, v70
	s_waitcnt vmcnt(17)
	v_mul_f32_e32 v46, 0xbfb8aa3b, v48
	v_addc_co_u32_e32 v35, vcc, 0, v71, vcc
	global_load_dwordx4 v[42:45], v[34:35], off
	v_add_co_u32_e32 v34, vcc, 0x1622000, v40
	v_exp_f32_e32 v84, v46
	s_nop 0
	v_addc_co_u32_e32 v35, vcc, 0, v41, vcc
	global_load_dwordx4 v[34:37], v[34:35], off
	s_waitcnt vmcnt(18)
	v_mul_f32_e32 v47, 0xbfb8aa3b, v47
	v_exp_f32_e32 v87, v47
	v_add_f32_e32 v89, 1.0, v84
	s_movk_i32 s4, 0x90
	v_frexp_mant_f32_e32 v47, v89
	v_add_f32_e32 v88, 1.0, v87
	s_lshl_b32 s39, s19, 6
	v_mul_lo_u32 v85, v38, s4
	v_cmp_gt_f32_e64 s[6:7], s72, v47
	v_frexp_mant_f32_e32 v47, v88
	v_and_b32_e32 v39, 0x1000, v39
	v_lshlrev_b32_e32 v83, 4, v123
	v_cmp_gt_f32_e64 s[4:5], s72, v47
	v_add3_u32 v47, 0, v85, v86
	s_cmp_eq_u32 s43, 0
	v_lshlrev_b32_e32 v38, 6, v38
	v_and_b32_e32 v46, 48, v83
	s_waitcnt vmcnt(17)
	ds_write_b128 v47, v[6:9]
	v_add_u32_e32 v6, 0, v39
	s_mov_b64 s[8:9], 0x380000
	s_cselect_b64 s[34:35], -1, 0
	s_cmp_lg_u32 s43, 0
	v_and_b32_e32 v79, 31, v123
	v_add3_u32 v6, v6, v38, v46
	v_lshl_add_u64 v[116:117], v[70:71], 0, s[8:9]
	s_cselect_b64 s[8:9], -1, 0
	s_and_b64 vcc, exec, s[34:35]
	s_waitcnt vmcnt(16)
	ds_write_b128 v6, v[2:5] offset:9216
	s_waitcnt vmcnt(15)
	ds_write_b128 v47, v[10:13] offset:17408
	s_waitcnt vmcnt(14)
	ds_write_b128 v6, v[14:17] offset:26624
	s_waitcnt vmcnt(13)
	ds_write_b128 v47, v[18:21] offset:34816
	s_waitcnt vmcnt(12)
	ds_write_b128 v6, v[22:25] offset:44032
	s_waitcnt vmcnt(11)
	ds_write_b128 v47, v[26:29] offset:52224
	s_waitcnt vmcnt(10)
	ds_write_b128 v6, v[30:33] offset:61440
	s_cbranch_vccnz .LBB0_2590
	v_add_co_u32_e32 v2, vcc, 0x6000, v116
	s_nop 1
	v_addc_co_u32_e32 v3, vcc, 0, v117, vcc
	global_load_dwordx4 v[46:49], v[2:3], off
